# MLA attention: q up-projection epilogue stores q pre-multiplied by scale*log2e (before the bf16 rounding); main loop restructured like the diff loop (reference max folded into the QK MFMA accumulator
# speedup vs baseline: 1.0500x; 1.0112x over previous
; #define LAS __attribute__((address_space(3)))
; DI void convert_layer(const Frame& F, int l) { for (int u = F.wg; u < CM_NPULL; u += F.nwg) convert_pull(F, l, u); }
; #define SEAM() do { if (a.fused) xcd_barrier(bar); } while (0)
; __global__ void __launch_bounds__(NTHREADS, 2) fwd(Args a) {
;     extern __shared__ __attribute__((aligned(16))) unsigned char lds_raw[];
;     ...
;     LAS unsigned char* lds0 = (LAS unsigned char*)lds_raw;
;     const int wave0 = __builtin_amdgcn_readfirstlane(threadIdx.x >> 6);
;     volatile LAS unsigned* xbw = (volatile LAS unsigned*)(lds0 + LDS_BYTES - 16);
;     if (threadIdx.x == 0) { xbw[0] = 0u; xbw[1] = 0u; xbw[2] = 0u; xbw[3] = 0u; }
;     __syncthreads();
;     XcdBarrier bar; bar.bar = (unsigned*)(a.ws + WS_CTL); bar.x = 0; bar.st = xbw;
;     if (a.fused) bar = xcd_barrier_post((unsigned*)(a.ws + WS_CTL), xbw);
;     ...
;     if (PIN(0)) { { FR(); convert_layer(F, 0); pro_gemv(F); } SEAM(); }
;     if (PIN(1)) { { FR(); pro_modreduce(F); } SEAM(); }
;     if (PIN(2)) { { FR(); pro_h0(F); } SEAM(); }
;     for (int l = a.l_lo; l < a.l_hi; ++l) {
.LBB0_257:
	s_load_dwordx4 s[8:11], s[0:1], 0xdc
	s_load_dwordx8 s[12:19], s[0:1], 0xb0
	v_mov_b32_e32 v1, 0
	v_mov_b32_e32 v232, 1
	v_mov_b32_e32 v233, 0x358637bd
	s_waitcnt lgkmcnt(0)
	s_cmp_lt_i32 s9, 1
	s_cselect_b64 s[2:3], -1, 0
	s_cmp_gt_i32 s10, 0
	s_cselect_b64 s[4:5], -1, 0
	s_and_b64 s[2:3], s[2:3], s[4:5]
	v_writelane_b32 v253, s2, 8
	s_load_dwordx2 s[4:5], s[0:1], 0xc8
	v_mov_b32_e32 v234, 0xc000
	v_writelane_b32 v253, s3, 9
	s_add_u32 s2, s0, 0xf0
	s_addc_u32 s3, s1, 0
	v_writelane_b32 v253, s2, 10
	s_cmp_lg_u32 s11, 0
	v_mov_b32_e32 v235, 0x3727c5ac
	v_writelane_b32 v253, s3, 11
	s_cselect_b64 s[2:3], -1, 0
	v_writelane_b32 v253, s2, 12
	v_mov_b32_e32 v236, 0x260
	v_mov_b32_e32 v237, 0x2e00
	v_writelane_b32 v253, s3, 13
	s_waitcnt lgkmcnt(0)
	s_add_u32 s2, s4, 0x200
	s_addc_u32 s3, s5, 0
	v_writelane_b32 v253, s2, 14
	v_mov_b32_e32 v238, 0x300
	v_mov_b32_e32 v239, 0xf149f2ca
	v_writelane_b32 v253, s3, 15
	s_add_u32 s2, s4, 0x1000
	s_addc_u32 s3, s5, 0
	v_writelane_b32 v253, s2, 16
	v_mov_b32_e32 v240, 0x318000
	v_mov_b32_e32 v241, 0x4200
	v_writelane_b32 v253, s3, 17
	s_add_u32 s2, s4, 0x1100
	s_addc_u32 s3, s5, 0
	v_writelane_b32 v253, s2, 18
	v_mov_b32_e32 v242, 0x7f800000
	v_mov_b64_e32 v[212:213], 0x3d0901
	v_writelane_b32 v253, s3, 19
	s_add_u32 s2, s4, 0x1200
	s_addc_u32 s3, s5, 0
	v_writelane_b32 v253, s2, 20
	v_mov_b32_e32 v243, 0x7fc00000
	s_movk_i32 s27, 0x180
	v_writelane_b32 v253, s3, 21
	s_add_u32 s2, s4, 0x1300
	s_addc_u32 s3, s5, 0
	v_writelane_b32 v253, s2, 22
	s_cmp_eq_u32 s33, 15
	s_mov_b32 s31, 0x2aaaaaab
	v_writelane_b32 v253, s3, 23
	s_cselect_b64 s[2:3], -1, 0
	v_writelane_b32 v253, s2, 24
	s_cmp_eq_u32 s33, 14
	s_movk_i32 s35, 0xff40
	v_writelane_b32 v253, s3, 25
	s_cselect_b64 s[2:3], -1, 0
	v_writelane_b32 v253, s2, 26
	s_cmp_eq_u32 s33, 13
	s_mov_b32 s96, 0x42ddb3d8
	v_writelane_b32 v253, s3, 27
	s_cselect_b64 s[2:3], -1, 0
	v_writelane_b32 v253, s2, 28
	s_cmp_eq_u32 s33, 12
	s_mov_b32 s97, 0x42fc0000
	v_writelane_b32 v253, s3, 29
	s_cselect_b64 s[2:3], -1, 0
	v_writelane_b32 v253, s2, 30
	s_cmp_eq_u32 s33, 11
	s_mov_b32 s79, 0x42fc6000
	v_writelane_b32 v253, s3, 31
	s_cselect_b64 s[2:3], -1, 0
	v_writelane_b32 v253, s2, 32
	s_cmp_eq_u32 s33, 10
	s_mov_b32 s26, 0x42800000
	v_writelane_b32 v253, s3, 33
	s_cselect_b64 s[2:3], -1, 0
	v_writelane_b32 v253, s2, 34
	s_cmp_eq_u32 s33, 9
	s_mov_b64 s[36:37], 0x80
	v_writelane_b32 v253, s3, 35
	s_cselect_b64 s[2:3], -1, 0
	v_writelane_b32 v253, s2, 36
	s_cmp_eq_u32 s33, 8
	s_mov_b32 s30, 1.0
	v_writelane_b32 v253, s3, 37
	s_cselect_b64 s[2:3], -1, 0
	v_writelane_b32 v253, s2, 38
	s_cmp_eq_u32 s33, 7
	s_mov_b64 s[52:53], 0xc000
	v_writelane_b32 v253, s3, 39
	s_cselect_b64 s[2:3], -1, 0
	v_writelane_b32 v253, s2, 40
	s_cmp_eq_u32 s33, 6
	s_mov_b64 s[54:55], 0x8000
	v_writelane_b32 v253, s3, 41
	s_cselect_b64 s[2:3], -1, 0
	v_writelane_b32 v253, s2, 42
	s_cmp_eq_u32 s33, 5
	s_mov_b32 s34, 1.0
	v_writelane_b32 v253, s3, 43
	s_cselect_b64 s[2:3], -1, 0
	v_writelane_b32 v253, s2, 44
	s_cmp_eq_u32 s33, 4
	s_nop 0
	v_writelane_b32 v253, s3, 45
	s_cselect_b64 s[2:3], -1, 0
	v_writelane_b32 v253, s2, 46
	s_cmp_eq_u32 s33, 3
	s_nop 0
	v_writelane_b32 v253, s3, 47
	s_cselect_b64 s[2:3], -1, 0
	v_writelane_b32 v253, s2, 48
	s_cmp_eq_u32 s33, 2
	s_nop 0
	v_writelane_b32 v253, s3, 49
	s_cselect_b64 s[2:3], -1, 0
	v_writelane_b32 v253, s2, 50
	s_cmp_eq_u32 s33, 1
	s_nop 0
	v_writelane_b32 v253, s3, 51
	s_cselect_b64 s[2:3], -1, 0
	v_writelane_b32 v253, s2, 52
	s_cmp_eq_u32 s33, 0
	s_nop 0
	v_writelane_b32 v253, s3, 53
	s_cselect_b64 s[2:3], -1, 0
	v_writelane_b32 v253, s2, 54
	s_nop 1
	v_writelane_b32 v253, s3, 55
	s_lshl_b32 s2, s33, 8
	s_add_u32 s2, s4, s2
	s_addc_u32 s3, s5, 0
	s_add_u32 s6, s2, 0x1400
	s_addc_u32 s7, s3, 0
	v_writelane_b32 v253, s6, 56
	s_add_u32 s2, s2, 0x2400
	s_addc_u32 s3, s3, 0
	v_writelane_b32 v253, s7, 57
	v_writelane_b32 v253, s2, 58
	s_movk_i32 s33, 0x2100
	s_nop 0
	v_writelane_b32 v253, s3, 59
	s_add_u32 s2, s4, 0x3400
	s_addc_u32 s3, s5, 0
	v_writelane_b32 v253, s2, 60
	s_nop 1
	v_writelane_b32 v253, s3, 61
	s_add_u32 s2, s4, 0x3500
	s_addc_u32 s3, s5, 0
	v_writelane_b32 v253, s2, 62
	s_cmp_lt_i32 s9, 2
	s_nop 0
	v_writelane_b32 v253, s3, 63
	s_cselect_b64 s[2:3], -1, 0
	s_cmp_gt_i32 s10, 1
	s_cselect_b64 s[4:5], -1, 0
	s_and_b64 s[2:3], s[2:3], s[4:5]
	v_writelane_b32 v254, s2, 0
	s_cmp_lt_i32 s9, 3
	s_nop 0
	v_writelane_b32 v254, s3, 1
	s_cselect_b64 s[2:3], -1, 0
	s_cmp_gt_i32 s10, 2
	s_cselect_b64 s[4:5], -1, 0
	s_and_b64 s[2:3], s[2:3], s[4:5]
	v_writelane_b32 v254, s2, 2
	s_cmp_lt_i32 s9, 5
	s_nop 0
	v_writelane_b32 v254, s3, 3
	s_cselect_b64 s[2:3], -1, 0
	s_cmp_gt_i32 s10, 4
	s_cselect_b64 s[4:5], -1, 0
	s_and_b64 s[2:3], s[2:3], s[4:5]
	v_writelane_b32 v254, s2, 4
	s_nop 1
	v_writelane_b32 v254, s3, 5
	s_add_u32 s2, s18, 0x4000
	v_writelane_b32 v254, s2, 6
	v_writelane_b32 v254, s12, 7
	s_addc_u32 s2, s19, 0
	s_cmp_lt_i32 s9, 9
	v_writelane_b32 v254, s13, 8
	v_writelane_b32 v254, s14, 9
	v_writelane_b32 v254, s15, 10
	v_writelane_b32 v254, s16, 11
	v_writelane_b32 v254, s17, 12
	v_writelane_b32 v254, s18, 13
	v_writelane_b32 v254, s19, 14
	v_writelane_b32 v254, s2, 15
	s_cselect_b64 s[2:3], -1, 0
	s_cmp_gt_i32 s10, 8
	s_cselect_b64 s[4:5], -1, 0
	s_and_b64 s[2:3], s[2:3], s[4:5]
	v_writelane_b32 v254, s2, 16
	s_cmp_lt_i32 s9, 10
	s_nop 0
	v_writelane_b32 v254, s3, 17
	s_cselect_b64 s[2:3], -1, 0
	s_cmp_gt_i32 s10, 9
	s_cselect_b64 s[4:5], -1, 0
	s_and_b64 s[2:3], s[2:3], s[4:5]
	v_writelane_b32 v254, s2, 18
	s_cmp_lt_i32 s9, 11
	s_nop 0
	v_writelane_b32 v254, s3, 19
	s_cselect_b64 s[2:3], -1, 0
	s_cmp_gt_i32 s10, 10
	s_cselect_b64 s[4:5], -1, 0
	s_and_b64 s[2:3], s[2:3], s[4:5]
	v_writelane_b32 v254, s2, 20
	s_cmp_lt_i32 s9, 12
	s_nop 0
	v_writelane_b32 v254, s3, 21
	s_cselect_b64 s[2:3], -1, 0
	s_cmp_gt_i32 s10, 11
	s_cselect_b64 s[4:5], -1, 0
	s_and_b64 s[2:3], s[2:3], s[4:5]
	v_writelane_b32 v254, s2, 22
	s_cmp_lt_i32 s9, 13
	s_nop 0
	v_writelane_b32 v254, s3, 23
	s_cselect_b64 s[2:3], -1, 0
	s_cmp_gt_i32 s10, 12
	s_cselect_b64 s[4:5], -1, 0
	s_and_b64 s[2:3], s[2:3], s[4:5]
	v_writelane_b32 v254, s2, 24
	s_cmp_lt_i32 s9, 14
	s_nop 0
	v_writelane_b32 v254, s3, 25
	s_cselect_b64 s[2:3], -1, 0
	s_cmp_gt_i32 s10, 13
	s_cselect_b64 s[4:5], -1, 0
	s_and_b64 s[2:3], s[2:3], s[4:5]
	v_writelane_b32 v254, s2, 26
	s_cmp_gt_i32 s9, 14
	s_nop 0
	v_writelane_b32 v254, s3, 27
	v_writelane_b32 v254, s8, 28
	s_cselect_b64 s[2:3], -1, 0
	s_cmp_lt_i32 s10, 15
	v_writelane_b32 v254, s9, 29
	v_writelane_b32 v254, s10, 30
	s_cselect_b64 s[4:5], -1, 0
	v_writelane_b32 v254, s11, 31
	s_or_b64 s[2:3], s[2:3], s[4:5]
	v_writelane_b32 v254, s2, 32
	s_load_dwordx16 s[4:19], s[0:1], 0x30
	s_nop 0
	v_writelane_b32 v254, s3, 33
	s_load_dwordx2 s[2:3], s[0:1], 0xd8
	s_waitcnt lgkmcnt(0)
; #define LAS __attribute__((address_space(3)))
; __global__ void __launch_bounds__(NTHREADS, 2) fwd(Args a) {
;     extern __shared__ __attribute__((aligned(16))) unsigned char lds_raw[];
;     ...
;     LAS unsigned char* lds0 = (LAS unsigned char*)lds_raw;
;     const int wave0 = __builtin_amdgcn_readfirstlane(threadIdx.x >> 6);
;     volatile LAS unsigned* xbw = (volatile LAS unsigned*)(lds0 + LDS_BYTES - 16);
;     if (threadIdx.x == 0) { xbw[0] = 0u; xbw[1] = 0u; xbw[2] = 0u; xbw[3] = 0u; }
;     __syncthreads();
;     XcdBarrier bar; bar.bar = (unsigned*)(a.ws + WS_CTL); bar.x = 0; bar.st = xbw;
;     if (a.fused) bar = xcd_barrier_post((unsigned*)(a.ws + WS_CTL), xbw);
	s_lshl_b32 s2, s2, 2
	v_writelane_b32 v254, s2, 34
	s_add_i32 s2, 0, 0x27ff0
	v_writelane_b32 v254, s2, 35
	s_add_i32 s2, 0, 0x27ff4
	v_writelane_b32 v254, s2, 36
	s_add_i32 s2, 0, 0x27fe0
	v_writelane_b32 v254, s2, 37
	s_add_i32 s2, 0, 0x14800
	v_writelane_b32 v254, s2, 38
	s_add_i32 s2, 0, 0x10800
	v_writelane_b32 v254, s2, 39
	s_add_i32 s2, 0, 0x10ba0
	v_writelane_b32 v254, s2, 40
	s_add_i32 s2, 0, 0x20010
	v_writelane_b32 v254, s2, 41
	s_add_i32 s2, 0, 0x20400
	v_writelane_b32 v254, s2, 42
	s_add_i32 s2, 0, 0x20410
	v_writelane_b32 v254, s2, 43
	s_add_i32 s2, 0, 0x20800
	v_writelane_b32 v254, s2, 44
	s_add_i32 s2, 0, 0x20810
	v_writelane_b32 v254, s2, 45
	v_writelane_b32 v254, s4, 46
	s_nop 1
	v_writelane_b32 v254, s5, 47
	v_writelane_b32 v254, s6, 48
	v_writelane_b32 v254, s7, 49
	v_writelane_b32 v254, s8, 50
	v_writelane_b32 v254, s9, 51
	v_writelane_b32 v254, s10, 52
	v_writelane_b32 v254, s11, 53
	v_writelane_b32 v254, s12, 54
	v_writelane_b32 v254, s13, 55
	v_writelane_b32 v254, s14, 56
	v_writelane_b32 v254, s15, 57
	v_writelane_b32 v254, s16, 58
	v_writelane_b32 v254, s17, 59
	v_writelane_b32 v254, s18, 60
	v_writelane_b32 v254, s19, 61
	s_load_dwordx16 s[4:19], s[0:1], 0x70
	s_waitcnt lgkmcnt(0)
	v_writelane_b32 v254, s4, 62
	s_nop 1
	v_writelane_b32 v255, s6, 0
	v_writelane_b32 v255, s7, 1
	v_writelane_b32 v255, s8, 2
	v_writelane_b32 v255, s9, 3
	v_writelane_b32 v255, s10, 4
	v_writelane_b32 v255, s11, 5
	v_writelane_b32 v255, s12, 6
	v_writelane_b32 v255, s13, 7
	v_writelane_b32 v255, s14, 8
	v_writelane_b32 v255, s15, 9
	v_writelane_b32 v255, s16, 10
	v_writelane_b32 v255, s17, 11
	v_writelane_b32 v255, s18, 12
	v_writelane_b32 v254, s5, 63
	v_writelane_b32 v255, s19, 13
	s_mov_b32 s9, 0
	s_branch .LBB0_261

; DI unsigned cvtpk(float lo, float hi) { const f32x2 v = {lo, hi}; const bf16x2n r = __builtin_convertvector(v, bf16x2n); return __builtin_bit_cast(unsigned, r); }
;     __device__ __forceinline__ void operator()(const f32x4 (&acc)[2][2][4][2], const Unit& u, int wr, int wc, int fr, int fq) const {
;         const int row0 = u.pm * BM + wr * 64 + fr; const int col0 = u.pn * BM + wc * 32 + 8 * fq;
; #pragma unroll
;         for (int ai = 0; ai < 2; ++ai)
; #pragma unroll
;             for (int m = 0; m < 4; ++m) { const int row = row0 + ai * HALF + m * 16; int b, tok; if (row < MLAT) { b = row >> 13; tok = CTX + (row & (SEQ - 1)); } else { b = (row - MLAT) >> 8; tok = (row - MLAT) & (CTX - 1); }
; #pragma unroll
;                 for (int bj = 0; bj < 2; ++bj) { const int col = col0 + bj * HALF; bf16_t* dst;
;                     if (mode == 0) { const int h = col / 192, d = col - h * 192; dst = Q + ((size_t)(b * 4 + h) * LTOT + tok) * 192 + d; }
;                     else { const int h = col >> 8, d = col & 255; dst = d < 128 ? K + ((size_t)(b * 4 + h) * LTOT + tok) * 192 + d : V + ((size_t)(b * 4 + h) * LTOT + tok) * 128 + (d - 128); }
;                     const f32x4 v0 = acc[ai][bj][m][0], v1 = acc[ai][bj][m][1];
;                     u32x4 w; w.x = cvtpk(v0[0], v0[1]); w.y = cvtpk(v0[2], v0[3]); w.z = cvtpk(v1[0], v1[1]); w.w = cvtpk(v1[2], v1[3]);
;                     *(u32x4*)dst = w; } }
;     }
.LBB0_541:
	v_mul_hi_i32 v145, v142, s31
	s_andn2_b64 vcc, exec, s[2:3]
	v_lshrrev_b32_e32 v164, 31, v145
	v_ashrrev_i32_e32 v165, 5, v145
	s_cbranch_vccnz .LBB0_543
	v_mul_f32_e32 v2, 0x3dd53b94, v2
	v_mul_f32_e32 v3, 0x3dd53b94, v3
	v_mul_f32_e32 v4, 0x3dd53b94, v4
	v_mul_f32_e32 v5, 0x3dd53b94, v5
	v_mul_f32_e32 v6, 0x3dd53b94, v6
	v_mul_f32_e32 v7, 0x3dd53b94, v7
	v_mul_f32_e32 v8, 0x3dd53b94, v8
	v_mul_f32_e32 v9, 0x3dd53b94, v9
	v_mul_f32_e32 v10, 0x3dd53b94, v10
	v_mul_f32_e32 v11, 0x3dd53b94, v11
	v_mul_f32_e32 v12, 0x3dd53b94, v12
	v_mul_f32_e32 v13, 0x3dd53b94, v13
	v_mul_f32_e32 v14, 0x3dd53b94, v14
	v_mul_f32_e32 v15, 0x3dd53b94, v15
	v_mul_f32_e32 v16, 0x3dd53b94, v16
	v_mul_f32_e32 v17, 0x3dd53b94, v17
	v_mul_f32_e32 v18, 0x3dd53b94, v18
	v_mul_f32_e32 v19, 0x3dd53b94, v19
	v_mul_f32_e32 v20, 0x3dd53b94, v20
	v_mul_f32_e32 v21, 0x3dd53b94, v21
	v_mul_f32_e32 v22, 0x3dd53b94, v22
	v_mul_f32_e32 v23, 0x3dd53b94, v23
	v_mul_f32_e32 v24, 0x3dd53b94, v24
	v_mul_f32_e32 v25, 0x3dd53b94, v25
	v_mul_f32_e32 v26, 0x3dd53b94, v26
	v_mul_f32_e32 v27, 0x3dd53b94, v27
	v_mul_f32_e32 v28, 0x3dd53b94, v28
	v_mul_f32_e32 v29, 0x3dd53b94, v29
	v_mul_f32_e32 v30, 0x3dd53b94, v30
	v_mul_f32_e32 v31, 0x3dd53b94, v31
	v_mul_f32_e32 v32, 0x3dd53b94, v32
	v_mul_f32_e32 v33, 0x3dd53b94, v33
	v_mul_f32_e32 v34, 0x3dd53b94, v34
	v_mul_f32_e32 v35, 0x3dd53b94, v35
	v_mul_f32_e32 v36, 0x3dd53b94, v36
	v_mul_f32_e32 v37, 0x3dd53b94, v37
	v_mul_f32_e32 v38, 0x3dd53b94, v38
	v_mul_f32_e32 v39, 0x3dd53b94, v39
	v_mul_f32_e32 v40, 0x3dd53b94, v40
	v_mul_f32_e32 v41, 0x3dd53b94, v41
	v_mul_f32_e32 v42, 0x3dd53b94, v42
	v_mul_f32_e32 v43, 0x3dd53b94, v43
	v_mul_f32_e32 v44, 0x3dd53b94, v44
	v_mul_f32_e32 v45, 0x3dd53b94, v45
	v_mul_f32_e32 v46, 0x3dd53b94, v46
	v_mul_f32_e32 v47, 0x3dd53b94, v47
	v_mul_f32_e32 v48, 0x3dd53b94, v48
	v_mul_f32_e32 v49, 0x3dd53b94, v49
	v_mul_f32_e32 v50, 0x3dd53b94, v50
	v_mul_f32_e32 v51, 0x3dd53b94, v51
	v_mul_f32_e32 v52, 0x3dd53b94, v52
	v_mul_f32_e32 v53, 0x3dd53b94, v53
	v_mul_f32_e32 v54, 0x3dd53b94, v54
	v_mul_f32_e32 v55, 0x3dd53b94, v55
	v_mul_f32_e32 v56, 0x3dd53b94, v56
	v_mul_f32_e32 v57, 0x3dd53b94, v57
	v_mul_f32_e32 v58, 0x3dd53b94, v58
	v_mul_f32_e32 v59, 0x3dd53b94, v59
	v_mul_f32_e32 v60, 0x3dd53b94, v60
	v_mul_f32_e32 v61, 0x3dd53b94, v61
	v_mul_f32_e32 v62, 0x3dd53b94, v62
	v_mul_f32_e32 v63, 0x3dd53b94, v63
	v_mul_f32_e32 v64, 0x3dd53b94, v64
	v_mul_f32_e32 v65, 0x3dd53b94, v65
	v_mul_f32_e32 v66, 0x3dd53b94, v66
	v_mul_f32_e32 v67, 0x3dd53b94, v67
	v_mul_f32_e32 v68, 0x3dd53b94, v68
	v_mul_f32_e32 v69, 0x3dd53b94, v69
	v_mul_f32_e32 v70, 0x3dd53b94, v70
	v_mul_f32_e32 v71, 0x3dd53b94, v71
	v_mul_f32_e32 v72, 0x3dd53b94, v72
	v_mul_f32_e32 v73, 0x3dd53b94, v73
	v_mul_f32_e32 v74, 0x3dd53b94, v74
	v_mul_f32_e32 v75, 0x3dd53b94, v75
	v_mul_f32_e32 v76, 0x3dd53b94, v76
	v_mul_f32_e32 v77, 0x3dd53b94, v77
	v_mul_f32_e32 v78, 0x3dd53b94, v78
	v_mul_f32_e32 v79, 0x3dd53b94, v79
	v_mul_f32_e32 v80, 0x3dd53b94, v80
	v_mul_f32_e32 v81, 0x3dd53b94, v81
	v_mul_f32_e32 v82, 0x3dd53b94, v82
	v_mul_f32_e32 v83, 0x3dd53b94, v83
	v_mul_f32_e32 v84, 0x3dd53b94, v84
	v_mul_f32_e32 v85, 0x3dd53b94, v85
	v_mul_f32_e32 v86, 0x3dd53b94, v86
	v_mul_f32_e32 v87, 0x3dd53b94, v87
	v_mul_f32_e32 v88, 0x3dd53b94, v88
	v_mul_f32_e32 v89, 0x3dd53b94, v89
	v_mul_f32_e32 v90, 0x3dd53b94, v90
	v_mul_f32_e32 v91, 0x3dd53b94, v91
	v_mul_f32_e32 v92, 0x3dd53b94, v92
	v_mul_f32_e32 v93, 0x3dd53b94, v93
	v_mul_f32_e32 v94, 0x3dd53b94, v94
	v_mul_f32_e32 v95, 0x3dd53b94, v95
	v_mul_f32_e32 v96, 0x3dd53b94, v96
	v_mul_f32_e32 v97, 0x3dd53b94, v97
	v_mul_f32_e32 v98, 0x3dd53b94, v98
	v_mul_f32_e32 v99, 0x3dd53b94, v99
	v_mul_f32_e32 v100, 0x3dd53b94, v100
	v_mul_f32_e32 v101, 0x3dd53b94, v101
	v_mul_f32_e32 v102, 0x3dd53b94, v102
	v_mul_f32_e32 v103, 0x3dd53b94, v103
	v_mul_f32_e32 v104, 0x3dd53b94, v104
	v_mul_f32_e32 v105, 0x3dd53b94, v105
	v_mul_f32_e32 v106, 0x3dd53b94, v106
	v_mul_f32_e32 v107, 0x3dd53b94, v107
	v_mul_f32_e32 v108, 0x3dd53b94, v108
	v_mul_f32_e32 v109, 0x3dd53b94, v109
	v_mul_f32_e32 v110, 0x3dd53b94, v110
	v_mul_f32_e32 v111, 0x3dd53b94, v111
	v_mul_f32_e32 v112, 0x3dd53b94, v112
	v_mul_f32_e32 v113, 0x3dd53b94, v113
	v_mul_f32_e32 v114, 0x3dd53b94, v114
	v_mul_f32_e32 v115, 0x3dd53b94, v115
	v_mul_f32_e32 v116, 0x3dd53b94, v116
	v_mul_f32_e32 v117, 0x3dd53b94, v117
	v_mul_f32_e32 v118, 0x3dd53b94, v118
	v_mul_f32_e32 v119, 0x3dd53b94, v119
	v_mul_f32_e32 v120, 0x3dd53b94, v120
	v_mul_f32_e32 v121, 0x3dd53b94, v121
	v_mul_f32_e32 v122, 0x3dd53b94, v122
	v_mul_f32_e32 v123, 0x3dd53b94, v123
	v_mul_f32_e32 v124, 0x3dd53b94, v124
	v_mul_f32_e32 v125, 0x3dd53b94, v125
	v_mul_f32_e32 v126, 0x3dd53b94, v126
	v_mul_f32_e32 v127, 0x3dd53b94, v127
	v_mul_f32_e32 v128, 0x3dd53b94, v128
	v_mul_f32_e32 v129, 0x3dd53b94, v129
	v_add_u32_e32 v145, v165, v164
	v_mad_u64_u32 v[148:149], s[2:3], v145, s35, v[142:143]
	v_add_u32_e32 v145, v166, v145
	v_mad_i64_i32 v[168:169], s[2:3], v145, s33, v[0:1]
	v_mov_b64_e32 v[170:171], s[6:7]
	v_mad_u64_u32 v[170:171], s[2:3], v168, s27, v[170:171]
	v_mad_i32_i24 v171, v169, s27, v171
	v_ashrrev_i32_e32 v149, 31, v148
	v_lshl_add_u64 v[148:149], v[148:149], 1, v[170:171]

; #define LAS __attribute__((address_space(3)))
; DI int v_st(int k, int c) { const int kk = (k & ~0xC) | ((k & 4) << 1) | ((k & 8) >> 1); return ((kk >> 3) * 4 + (c >> 5)) * 512 + ((kk & 7) * 32 + (c & 31)) * 2; }
; DI int v_rd_base(int lane) { return ((lane & 3) << 3) | (((lane >> 2) & 3) << 6) | (((lane >> 4) & 1) << 5) | (((lane >> 5) & 1) << 8); }
; #define SLOAD(i, k0) do { sr_[i].vs0 = *reinterpret_cast<const bf16x8*>(&Vh[(long)((k0) + sr) * DV + sc]); sr_[i].vs1 = *reinterpret_cast<const bf16x8*>(&Vh[(long)((k0) + 32 + sr) * DV + sc]); \
;     _Pragma("unroll") for (int _c = 0; _c < NKC; ++_c) sr_[i].ks[_c] = *reinterpret_cast<const bf16x8*>(&Kh[(long)((k0) + krow[_c]) * DQK + kcol[_c]]); } while (0)
; #define SWRITE(b, i) do { *(LAS bf16x8*)(V_lds + (b) * SHM_V + vst0) = sr_[i].vs0; *(LAS bf16x8*)(V_lds + (b) * SHM_V + vst1) = sr_[i].vs1; \
;     _Pragma("unroll") for (int _c = 0; _c < NKC; ++_c) *(LAS bf16x8*)(K_lds + (b) * SHM_K + kswz<DQK>(krow[_c], kcol[_c] * 2)) = sr_[i].ks[_c]; } while (0)
; #define SWAIT() do { if constexpr (SDEPTH == 2) { if constexpr (NKC == 1) asm volatile("s_waitcnt vmcnt(3)" ::: "memory"); else if constexpr (NKC == 2) asm volatile("s_waitcnt vmcnt(4)" ::: "memory"); else asm volatile("s_waitcnt vmcnt(5)" ::: "memory"); } \
;     else asm volatile("s_waitcnt vmcnt(0)" ::: "memory"); } while (0)
; template <int DQK, int SDEPTH, bool OUT_BF16, int QREG = DQK / 16, bool OUT_F16 = false> ...
;     ...
;       for (int d0 = 0; d0 < 4; ++d0) *(LAS u32x4*)(Qp + (8 - QREG + d0) * 1024) = f[d0];
;     }
;   }
;     ...
;   const int sr = tid >> 4, sc = (tid & 15) * 8, vst0 = v_st(sr, sc), vst1 = v_st(32 + sr, sc);
;   int krow[NKC], kcol[NKC];
; #pragma unroll
;   for (int i = 0; i < NKC; ++i) { const int ci = tid + i * 512; krow[i] = ci / CPR; kcol[i] = (ci % CPR) * 8; }
;   const int vb0 = (int)(uintptr_t)V_lds + v_rd_base(lane);
;   struct { bf16x8 vs0, vs1, ks[NKC]; } sr_[SDEPTH];
;     ...
;   f32x16 pA0, pA1, pB0, pB1; float mnA, mnB, alA, alB; bf16x8 pa0, pa1, pa2, pa3; const int NT = seq / KVBLK;
;   constexpr int SE = 0, SO = SDEPTH - 1;
;   SLOAD(SE, 0); asm volatile("s_waitcnt vmcnt(0)" ::: "memory"); SWRITE(0, SE); __syncthreads();
;   QKT(pA0, pA1, K_lds); partialSM(pA0, pA1, m_reg, mnA, alA, SCALE);
;   SLOAD(SO, KVBLK); if constexpr (SDEPTH == 2) { if (2 < NT) SLOAD(SE, 2 * KVBLK); }
;   SWAIT(); SWRITE(1, SO); __syncthreads();
.LBB0_747:
	s_waitcnt vmcnt(3)
	ds_write_b128 v162, v[2:5] offset:4096
	s_waitcnt vmcnt(2)
	ds_write_b128 v162, v[6:9] offset:5120
	s_waitcnt vmcnt(1)
	ds_write_b128 v162, v[10:13] offset:6144
	s_waitcnt vmcnt(0)
	ds_write_b128 v162, v[14:17] offset:7168
	v_ashrrev_i32_e32 v2, 4, v34
	v_and_b32_e32 v5, 0xfffff0, v2
	v_lshlrev_b32_e32 v6, 1, v2
	v_lshlrev_b32_e32 v3, 3, v84
	v_and_or_b32 v5, v6, 8, v5
	v_and_b32_e32 v4, 0x78, v3
	v_lshrrev_b32_e32 v5, 1, v5
	v_bfe_u32 v3, v3, 5, 2
	v_or_b32_e32 v5, v5, v3
	v_lshrrev_b32_e32 v6, 1, v2
	v_lshlrev_b32_e32 v22, 9, v5
	v_and_b32_e32 v5, 3, v2
	v_and_or_b32 v5, v6, 4, v5
	v_add_u32_e32 v6, 32, v2
	v_and_b32_e32 v7, 0xfffff0, v6
	v_lshlrev_b32_e32 v8, 1, v6
	v_and_or_b32 v7, v8, 8, v7
	v_lshrrev_b32_e32 v7, 1, v7
	v_or_b32_e32 v3, v7, v3
	v_mul_hi_i32 v7, v34, s31
	v_lshrrev_b32_e32 v8, 31, v7
	v_ashrrev_i32_e32 v7, 2, v7
	v_add_u32_e32 v58, v7, v8
	v_mul_lo_u32 v7, v58, 24
	v_sub_u32_e32 v24, v34, v7
	v_add_u32_e32 v7, 0x200, v34
	v_mul_hi_i32 v8, v7, s31
	v_lshrrev_b32_e32 v9, 31, v8
	v_ashrrev_i32_e32 v8, 2, v8
	v_add_u32_e32 v62, v8, v9
	v_mul_lo_u32 v8, v62, 24
	v_sub_u32_e32 v25, v7, v8
	v_add_u32_e32 v7, 0x400, v34
	v_mul_hi_i32 v8, v7, s31
	v_lshrrev_b32_e32 v9, 31, v8
	v_ashrrev_i32_e32 v8, 2, v8
	v_lshlrev_b32_e32 v23, 6, v5
	v_lshlrev_b32_e32 v5, 4, v84
	v_add_u32_e32 v68, v8, v9
	s_mul_i32 s1, s38, 0x210000
	v_lshlrev_b32_e32 v3, 9, v3
	v_mul_lo_u32 v8, v68, 24
	v_and_b32_e32 v27, 48, v5
	s_mul_hi_i32 s0, s38, 0x210000
	s_add_u32 s1, s4, s1
	v_sub_u32_e32 v26, v7, v8
	v_or3_b32 v28, v3, v23, v27
	v_lshlrev_b32_e32 v3, 3, v85
	v_and_b32_e32 v5, 0xc0, v35
	v_lshlrev_b32_e32 v7, 1, v85
	s_addc_u32 s0, s5, s0
	v_and_or_b32 v5, v3, 24, v5
	v_and_b32_e32 v7, 32, v7
	v_and_b32_e32 v3, 0x100, v3
	s_add_u32 s2, s1, 0x44874000
	v_or3_b32 v86, v5, v7, v3
	v_ashrrev_i32_e32 v3, 31, v2
	s_addc_u32 s3, s0, 0
	v_lshlrev_b64 v[70:71], 8, v[2:3]
	v_lshl_add_u64 v[2:3], s[2:3], 0, v[70:71]
	v_lshlrev_b32_e32 v8, 1, v4
	v_mov_b32_e32 v9, v1
	v_lshl_add_u64 v[54:55], v[2:3], 0, v[8:9]
	s_mul_i32 s1, s38, 0x318000
	global_load_dwordx4 v[2:5], v[54:55], off
	s_mul_hi_i32 s0, s38, 0x318000
	s_add_u32 s1, s4, s1
	s_addc_u32 s8, s5, s0
	s_add_u32 s0, s1, 0x42fb4000
	s_addc_u32 s1, s8, 0
	v_and_b32_e32 v18, 0x3fffffc0, v34
	s_add_i32 s8, 0, 0x14000
	v_lshl_add_u32 v143, v18, 2, s8
	v_lshlrev_b32_e32 v10, 3, v24
	v_lshlrev_b32_e32 v14, 3, v25
	v_lshlrev_b32_e32 v18, 3, v26
	v_ashrrev_i32_e32 v7, 31, v6
	v_lshlrev_b64 v[6:7], 8, v[6:7]
	v_ashrrev_i32_e32 v11, 31, v10
	v_mov_b64_e32 v[66:67], s[0:1]
	v_ashrrev_i32_e32 v15, 31, v14
	v_ashrrev_i32_e32 v19, 31, v18
	v_lshl_add_u64 v[6:7], s[2:3], 0, v[6:7]
	v_mad_i64_i32 v[12:13], s[0:1], v58, s27, v[66:67]
	v_lshlrev_b64 v[74:75], 1, v[10:11]
	v_mad_i64_i32 v[16:17], s[0:1], v62, s27, v[66:67]
	v_lshlrev_b64 v[78:79], 1, v[14:15]
	v_mad_i64_i32 v[20:21], s[0:1], v68, s27, v[66:67]
	v_lshlrev_b64 v[82:83], 1, v[18:19]
	v_lshl_add_u64 v[6:7], v[6:7], 0, v[8:9]
	v_lshl_add_u64 v[10:11], v[12:13], 0, v[74:75]
	v_lshl_add_u64 v[14:15], v[16:17], 0, v[78:79]
	v_lshl_add_u64 v[18:19], v[20:21], 0, v[82:83]
	global_load_dwordx4 v[6:9], v[6:7], off
	v_or3_b32 v22, v22, v23, v27
	global_load_dwordx4 v[10:13], v[10:11], off
	v_add_u32_e32 v167, 0, v22
	global_load_dwordx4 v[14:17], v[14:15], off
	v_mad_i64_i32 v[72:73], s[2:3], v58, s27, 0
	global_load_dwordx4 v[18:21], v[18:19], off
	s_waitcnt vmcnt(0)
	v_mad_i64_i32 v[76:77], s[0:1], v62, s27, 0
	v_mad_i64_i32 v[80:81], s[0:1], v68, s27, 0
	v_mad_u32_u24 v57, v160, s27, 0
	v_add_u32_e32 v168, 0, v28
	v_or_b32_e32 v50, 32, v0
	s_movk_i32 s0, 0x4000
	s_mov_b32 s8, s9
	s_mov_b32 s10, s9
	s_mov_b32 s11, s9
	s_mov_b32 s12, s9
	s_mov_b32 s13, s9
	s_mov_b32 s14, s9
	s_mov_b32 s15, s9
	s_mov_b32 s16, s9
	s_mov_b32 s17, s9
	s_mov_b32 s18, s9
	s_mov_b32 s19, s9
	s_mov_b32 s20, s9
	s_mov_b32 s21, s9
	s_mov_b32 s22, s9
	s_mov_b32 s23, s9
	s_mov_b32 s41, 2
	v_add_u32_e32 v163, 0, v86
	v_lshl_add_u32 v164, v160, 2, v143
	v_mov_b32_e32 v166, 0
	s_waitcnt vmcnt(4)
	ds_write_b128 v167, v[2:5]
	v_bitop3_b32 v2, v58, v24, 7 bitop3:0x6c
	v_lshl_add_u32 v2, v2, 4, 0
	v_add_u32_e32 v169, v2, v72
	v_bitop3_b32 v2, v62, v25, 7 bitop3:0x6c
	v_lshl_add_u32 v2, v2, 4, 0
	v_add_u32_e32 v170, v2, v76
	v_bitop3_b32 v2, v68, v26, 7 bitop3:0x6c
	v_lshl_add_u32 v2, v2, 4, 0
	v_add_u32_e32 v171, v2, v80
	v_lshlrev_b32_e32 v2, 4, v160
	v_and_b32_e32 v56, 0x70, v2
	v_xad_u32 v172, v0, v56, v57
	v_xad_u32 v173, v50, v56, v57
	v_add_u32_e32 v58, 64, v58
	v_add_u32_e32 v62, 64, v62
	v_add_u32_e32 v68, 64, v68
	v_add_u32_e32 v196, 0xe000, v172
	v_add_u32_e32 v195, 0xe000, v173
	s_waitcnt vmcnt(3)
	ds_write_b128 v168, v[6:9]
	s_waitcnt vmcnt(2)
	ds_write_b128 v169, v[10:13] offset:32768
	s_waitcnt vmcnt(1)
	ds_write_b128 v170, v[14:17] offset:32768
	v_mov_b64_e32 v[2:3], s[8:9]
	v_mov_b64_e32 v[16:17], s[22:23]
	s_waitcnt vmcnt(0)
	ds_write_b128 v171, v[18:21] offset:32768
	s_waitcnt lgkmcnt(0)
	s_barrier
; DI int v_st(int k, int c) { const int kk = (k & ~0xC) | ((k & 4) << 1) | ((k & 8) >> 1); return ((kk >> 3) * 4 + (c >> 5)) * 512 + ((kk & 7) * 32 + (c & 31)) * 2; }
; DI int v_rd_base(int lane) { return ((lane & 3) << 3) | (((lane >> 2) & 3) << 6) | (((lane >> 4) & 1) << 5) | (((lane >> 5) & 1) << 8); }
; #define SLOAD(i, k0) do { sr_[i].vs0 = *reinterpret_cast<const bf16x8*>(&Vh[(long)((k0) + sr) * DV + sc]); sr_[i].vs1 = *reinterpret_cast<const bf16x8*>(&Vh[(long)((k0) + 32 + sr) * DV + sc]); \
;     _Pragma("unroll") for (int _c = 0; _c < NKC; ++_c) sr_[i].ks[_c] = *reinterpret_cast<const bf16x8*>(&Kh[(long)((k0) + krow[_c]) * DQK + kcol[_c]]); } while (0)
; #define SWRITE(b, i) do { *(LAS bf16x8*)(V_lds + (b) * SHM_V + vst0) = sr_[i].vs0; *(LAS bf16x8*)(V_lds + (b) * SHM_V + vst1) = sr_[i].vs1; \
;     _Pragma("unroll") for (int _c = 0; _c < NKC; ++_c) *(LAS bf16x8*)(K_lds + (b) * SHM_K + kswz<DQK>(krow[_c], kcol[_c] * 2)) = sr_[i].ks[_c]; } while (0)
; template <int DQK, int SDEPTH, bool OUT_BF16, int QREG = DQK / 16, bool OUT_F16 = false> ...
;     ...
;   const int sr = tid >> 4, sc = (tid & 15) * 8, vst0 = v_st(sr, sc), vst1 = v_st(32 + sr, sc);
;   int krow[NKC], kcol[NKC];
; #pragma unroll
;   for (int i = 0; i < NKC; ++i) { const int ci = tid + i * 512; krow[i] = ci / CPR; kcol[i] = (ci % CPR) * 8; }
;   const int vb0 = (int)(uintptr_t)V_lds + v_rd_base(lane);
;   struct { bf16x8 vs0, vs1, ks[NKC]; } sr_[SDEPTH];
;     ...
;   f32x16 pA0, pA1, pB0, pB1; float mnA, mnB, alA, alB; bf16x8 pa0, pa1, pa2, pa3; const int NT = seq / KVBLK;
;   constexpr int SE = 0, SO = SDEPTH - 1;
;   SLOAD(SE, 0); asm volatile("s_waitcnt vmcnt(0)" ::: "memory"); SWRITE(0, SE); __syncthreads();
;   QKT(pA0, pA1, K_lds); partialSM(pA0, pA1, m_reg, mnA, alA, SCALE);
;   SLOAD(SO, KVBLK); if constexpr (SDEPTH == 2) { if (2 < NT) SLOAD(SE, 2 * KVBLK); }
	ds_read_b128 v[18:21], v172 offset:32768
	ds_read_b128 v[22:25], v172 offset:45056
	s_waitcnt lgkmcnt(1)
	v_mfma_f32_32x32x16_bf16 v[34:49], v[18:21], v[110:113], 0
	ds_read_b128 v[50:53], v173 offset:32768
	ds_read_b128 v[88:91], v173 offset:45056
	v_mov_b64_e32 v[4:5], s[10:11]
	v_mov_b64_e32 v[6:7], s[12:13]
	v_mov_b64_e32 v[8:9], s[14:15]
	v_mov_b64_e32 v[10:11], s[16:17]
	v_mov_b64_e32 v[12:13], s[18:19]
	v_mov_b64_e32 v[14:15], s[20:21]
	s_waitcnt lgkmcnt(2)
	v_mfma_f32_32x32x16_bf16 v[18:33], v[22:25], v[110:113], 0
	s_waitcnt lgkmcnt(1)
	v_mfma_f32_32x32x16_bf16 v[34:49], v[50:53], v[106:109], v[34:49]
	v_or_b32_e32 v50, 64, v0
	v_xad_u32 v174, v50, v56, v57
	v_add_u32_e32 v193, 0xe000, v174
	s_waitcnt lgkmcnt(0)
	v_mfma_f32_32x32x16_bf16 v[18:33], v[88:91], v[106:109], v[18:33]
	ds_read_b128 v[50:53], v174 offset:32768
	ds_read_b128 v[88:91], v174 offset:45056
	s_waitcnt lgkmcnt(1)
	v_mfma_f32_32x32x16_bf16 v[34:49], v[50:53], v[102:105], v[34:49]
	v_or_b32_e32 v50, 0x60, v0
	v_xad_u32 v175, v50, v56, v57
	v_add_u32_e32 v192, 0xe000, v175
	s_waitcnt lgkmcnt(0)
	v_mfma_f32_32x32x16_bf16 v[18:33], v[88:91], v[102:105], v[18:33]
	ds_read_b128 v[50:53], v175 offset:32768
	ds_read_b128 v[88:91], v175 offset:45056
	s_waitcnt lgkmcnt(1)
	v_mfma_f32_32x32x16_bf16 v[34:49], v[50:53], v[98:101], v[34:49]
	v_or_b32_e32 v50, 0x80, v0
	v_xad_u32 v176, v50, v56, v57
	v_add_u32_e32 v191, 0xe000, v176
	s_waitcnt lgkmcnt(0)
	v_mfma_f32_32x32x16_bf16 v[18:33], v[88:91], v[98:101], v[18:33]
	ds_read_b128 v[50:53], v176 offset:32768
	ds_read_b128 v[88:91], v176 offset:45056
	ds_read_b128 v[92:95], v162
	s_waitcnt lgkmcnt(0)
	v_mfma_f32_32x32x16_bf16 v[34:49], v[50:53], v[92:95], v[34:49]
	v_or_b32_e32 v50, 0xa0, v0
	v_xad_u32 v177, v50, v56, v57
	v_add_u32_e32 v190, 0xe000, v177
	v_mfma_f32_32x32x16_bf16 v[18:33], v[88:91], v[92:95], v[18:33]
	ds_read_b128 v[50:53], v177 offset:32768
	ds_read_b128 v[88:91], v177 offset:45056
	ds_read_b128 v[92:95], v162 offset:1024
	s_waitcnt lgkmcnt(0)
	v_mfma_f32_32x32x16_bf16 v[34:49], v[50:53], v[92:95], v[34:49]
	v_or_b32_e32 v50, 0xc0, v0
	v_xad_u32 v178, v50, v56, v57
	v_add_u32_e32 v189, 0xe000, v178
	v_mfma_f32_32x32x16_bf16 v[18:33], v[88:91], v[92:95], v[18:33]
	ds_read_b128 v[50:53], v178 offset:32768
	ds_read_b128 v[88:91], v178 offset:45056
	ds_read_b128 v[92:95], v162 offset:2048
	s_waitcnt lgkmcnt(0)
	v_mfma_f32_32x32x16_bf16 v[34:49], v[50:53], v[92:95], v[34:49]
	v_or_b32_e32 v50, 0xe0, v0
	v_xad_u32 v179, v50, v56, v57
	v_add_u32_e32 v188, 0xe000, v179
	v_mfma_f32_32x32x16_bf16 v[18:33], v[88:91], v[92:95], v[18:33]
	ds_read_b128 v[50:53], v179 offset:32768
	ds_read_b128 v[88:91], v179 offset:45056
	ds_read_b128 v[92:95], v162 offset:3072
	s_waitcnt lgkmcnt(0)
	v_mfma_f32_32x32x16_bf16 v[34:49], v[50:53], v[92:95], v[34:49]
	v_or_b32_e32 v50, 0x100, v0
	v_xad_u32 v180, v50, v56, v57
	v_add_u32_e32 v187, 0xe000, v180
	v_mfma_f32_32x32x16_bf16 v[18:33], v[88:91], v[92:95], v[18:33]
	ds_read_b128 v[50:53], v180 offset:32768
	ds_read_b128 v[88:91], v180 offset:45056
	ds_read_b128 v[92:95], v162 offset:4096
	s_waitcnt lgkmcnt(0)
	v_mfma_f32_32x32x16_bf16 v[34:49], v[50:53], v[92:95], v[34:49]
	v_or_b32_e32 v50, 0x120, v0
	v_xad_u32 v181, v50, v56, v57
	v_add_u32_e32 v186, 0xe000, v181
	v_mfma_f32_32x32x16_bf16 v[18:33], v[88:91], v[92:95], v[18:33]
	ds_read_b128 v[50:53], v181 offset:32768
	ds_read_b128 v[88:91], v181 offset:45056
	ds_read_b128 v[92:95], v162 offset:5120
	s_waitcnt lgkmcnt(0)
	v_mfma_f32_32x32x16_bf16 v[34:49], v[50:53], v[92:95], v[34:49]
	v_or_b32_e32 v50, 0x140, v0
	v_xad_u32 v182, v50, v56, v57
	v_add_u32_e32 v185, 0xe000, v182
	v_mfma_f32_32x32x16_bf16 v[18:33], v[88:91], v[92:95], v[18:33]
	ds_read_b128 v[50:53], v182 offset:32768
	ds_read_b128 v[88:91], v182 offset:45056
	ds_read_b128 v[92:95], v162 offset:6144
	s_waitcnt lgkmcnt(0)
	v_mfma_f32_32x32x16_bf16 v[34:49], v[50:53], v[92:95], v[34:49]
	v_or_b32_e32 v50, 0x160, v0
	v_xad_u32 v183, v50, v56, v57
	v_add_u32_e32 v184, 0xe000, v183
	v_mfma_f32_32x32x16_bf16 v[18:33], v[88:91], v[92:95], v[18:33]
	ds_read_b128 v[50:53], v183 offset:32768
	ds_read_b128 v[88:91], v183 offset:45056
	ds_read_b128 v[92:95], v162 offset:7168
	s_waitcnt lgkmcnt(0)
	v_mfma_f32_32x32x16_bf16 v[34:49], v[50:53], v[92:95], v[34:49]
	v_mfma_f32_32x32x16_bf16 v[18:33], v[88:91], v[92:95], v[18:33]
	s_nop 10
	v_max_f32_e32 v50, v35, v35
	v_max_f32_e32 v51, v34, v34
	v_max_f32_e32 v50, v51, v50
	v_max3_f32 v50, v50, v36, v37
	v_max3_f32 v50, v50, v38, v39
	v_max3_f32 v50, v50, v40, v41
	v_max3_f32 v50, v50, v42, v43
	v_max3_f32 v50, v50, v44, v45
	v_max3_f32 v50, v50, v46, v47
	v_max3_f32 v50, v50, v48, v49
	v_max3_f32 v50, v50, v18, v19
	v_max3_f32 v50, v50, v20, v21
	v_max3_f32 v50, v50, v22, v23
	v_max3_f32 v50, v50, v24, v25
	v_max3_f32 v50, v50, v26, v27
	v_max3_f32 v50, v50, v28, v29
	v_max3_f32 v50, v50, v30, v31
	v_max3_f32 v50, v50, v32, v33
	v_mov_b32_e32 v51, v50
	s_nop 1
	v_permlane32_swap_b32_e32 v50, v51
	v_max_f32_e32 v51, v51, v51
	v_max_f32_e32 v50, v50, v50
	v_max_f32_e32 v87, v50, v51
	v_add_f32_e32 v50, 0x7149f2ca, v87
	v_cmp_ge_f32_e32 vcc, 0x4138aa3b, v50
	v_add_co_u32_e64 v50, s[0:1], s0, v54
	s_cmp_eq_u64 vcc, exec
	s_nop 0
	v_addc_co_u32_e64 v51, s[0:1], 0, v55, s[0:1]
	s_movk_i32 s0, 0x6000
	s_nop 0
	v_add_co_u32_e64 v54, s[0:1], s0, v54
	global_load_dwordx4 v[50:53], v[50:51], off
	s_nop 0
	v_addc_co_u32_e64 v55, s[0:1], 0, v55, s[0:1]
	v_mad_i64_i32 v[58:59], s[0:1], v58, s27, v[66:67]
	global_load_dwordx4 v[54:57], v[54:55], off
	v_lshl_add_u64 v[58:59], v[58:59], 0, v[74:75]
	v_mad_i64_i32 v[62:63], s[0:1], v62, s27, v[66:67]
	global_load_dwordx4 v[58:61], v[58:59], off
	v_lshl_add_u64 v[62:63], v[62:63], 0, v[78:79]
	v_mad_i64_i32 v[66:67], s[0:1], v68, s27, v[66:67]
	global_load_dwordx4 v[62:65], v[62:63], off
	v_lshl_add_u64 v[66:67], v[66:67], 0, v[82:83]
	global_load_dwordx4 v[66:69], v[66:67], off
	s_waitcnt vmcnt(0)
; DI void partialSM(f32x16& p0, f32x16& p1, float& m_reg, float& mn, float& alpha, const float SCALE) {
;     ...
;   if (__builtin_expect(__all(pmax - m_reg <= THR / SCALE), 1)) { mn = m_reg; alpha = 1.f; }
;   else { mn = fmaxf(m_reg, pmax); alpha = __builtin_amdgcn_exp2f((m_reg - mn) * C); m_reg = mn; }
;   const float mnC = -mn * C;
; #pragma unroll
;   for (int r = 0; r < 16; ++r) p0[r] = fmaf(p0[r], C, mnC);
; #pragma unroll
;   for (int r = 0; r < 16; ++r) p1[r] = fmaf(p1[r], C, mnC);
; #pragma unroll
;   for (int r = 0; r < 16; ++r) p0[r] = __builtin_amdgcn_exp2f(p0[r]);
; }
; DI void finishSM(f32x16& p0, f32x16& p1, float alpha, float& l_reg, bf16x8& pa0, bf16x8& pa1, bf16x8& pa2, bf16x8& pa3) {
; #pragma unroll
;   for (int r = 0; r < 16; ++r) p1[r] = __builtin_amdgcn_exp2f(p1[r]);
;   float ps = 0;
; #pragma unroll
;   for (int r = 0; r < 16; ++r) ps += p0[r];
; #pragma unroll
;   for (int r = 0; r < 16; ++r) ps += p1[r];
;   { auto rr = __builtin_amdgcn_permlane32_swap(__float_as_uint(ps), __float_as_uint(ps), false, false);
;     ps = __uint_as_float(rr[0]) + __uint_as_float(rr[1]); }
;   l_reg = l_reg * alpha + ps;
	s_waitcnt vmcnt(4)
	ds_write_b128 v167, v[50:53] offset:16384
	s_waitcnt vmcnt(3)
	ds_write_b128 v168, v[54:57] offset:16384
	s_waitcnt vmcnt(2)
	ds_write_b128 v169, v[58:61] offset:57344
	s_waitcnt vmcnt(1)
	ds_write_b128 v170, v[62:65] offset:57344
	s_waitcnt vmcnt(0)
	ds_write_b128 v171, v[66:69] offset:57344
	s_cselect_b64 vcc, -1, 0
	v_max_f32_e32 v51, 0xf149f2ca, v87
	v_cndmask_b32_e32 v194, v51, v239, vcc
	v_mul_f32_e32 v50, 0xbf800000, v194
	v_fmamk_f32 v34, v34, 0x3f800000, v50
	v_exp_f32_e32 v134, v34
	v_fmamk_f32 v34, v35, 0x3f800000, v50
	v_exp_f32_e32 v135, v34
	v_fmamk_f32 v34, v36, 0x3f800000, v50
	v_exp_f32_e32 v136, v34
	v_fmamk_f32 v34, v37, 0x3f800000, v50
	v_exp_f32_e32 v138, v34
	v_fmamk_f32 v34, v38, 0x3f800000, v50
	v_exp_f32_e32 v155, v34
	v_fmamk_f32 v34, v39, 0x3f800000, v50
	v_exp_f32_e32 v156, v34
	v_fmamk_f32 v34, v40, 0x3f800000, v50
	v_exp_f32_e32 v137, v34
	v_fmamk_f32 v34, v41, 0x3f800000, v50
	v_pk_fma_f32 v[126:127], v[18:19], s[30:31], v[50:51] op_sel_hi:[1,0,0]
	v_sub_f32_e32 v18, 0xf149f2ca, v51
	v_exp_f32_e32 v154, v34
	v_fmamk_f32 v34, v42, 0x3f800000, v50
	v_mul_f32_e32 v18, 0x3f800000, v18
	v_exp_f32_e32 v131, v34
	v_fmamk_f32 v34, v43, 0x3f800000, v50
	v_exp_f32_e32 v18, v18
	v_exp_f32_e32 v133, v34
	v_fmamk_f32 v34, v44, 0x3f800000, v50
	v_exp_f32_e32 v139, v34
	v_fmamk_f32 v34, v45, 0x3f800000, v50
	v_exp_f32_e32 v152, v34
	v_fmamk_f32 v34, v46, 0x3f800000, v50
	s_add_i32 s2, 0, 0x4000
	v_exp_f32_e32 v132, v34
	v_fmamk_f32 v34, v47, 0x3f800000, v50
	v_cndmask_b32_e64 v197, v18, 1.0, vcc
	v_add_u32_e32 v165, s2, v86
	v_mad_i64_i32 v[18:19], s[2:3], s38, v240, v[80:81]
	v_exp_f32_e32 v140, v34
	v_fmamk_f32 v34, v48, 0x3f800000, v50
	v_lshl_add_u64 v[144:145], v[18:19], 0, v[82:83]
	v_mad_i64_i32 v[18:19], s[2:3], s38, v240, v[76:77]
	v_exp_f32_e32 v141, v34
	v_fmamk_f32 v34, v49, 0x3f800000, v50
	v_lshl_add_u64 v[146:147], v[18:19], 0, v[78:79]
	v_mad_i64_i32 v[18:19], s[2:3], s38, v240, v[72:73]
	v_exp_f32_e32 v153, v34
	v_lshl_add_u64 v[148:149], v[18:19], 0, v[74:75]
	v_mov_b32_e32 v18, 0x210000
	v_mad_i64_i32 v[150:151], s[2:3], s38, v18, v[70:71]
	v_and_b32_e32 v18, 15, v84
	v_pk_fma_f32 v[114:115], v[32:33], s[30:31], v[50:51] op_sel_hi:[1,0,0]
	v_pk_fma_f32 v[120:121], v[30:31], s[30:31], v[50:51] op_sel_hi:[1,0,0]
	v_pk_fma_f32 v[128:129], v[28:29], s[30:31], v[50:51] op_sel_hi:[1,0,0]
	v_pk_fma_f32 v[116:117], v[26:27], s[30:31], v[50:51] op_sel_hi:[1,0,0]
	v_pk_fma_f32 v[118:119], v[24:25], s[30:31], v[50:51] op_sel_hi:[1,0,0]
	v_pk_fma_f32 v[122:123], v[22:23], s[30:31], v[50:51] op_sel_hi:[1,0,0]
	v_pk_fma_f32 v[124:125], v[20:21], s[30:31], v[50:51] op_sel_hi:[1,0,0]
	v_lshl_or_b32 v150, v18, 4, v150
	v_mov_b64_e32 v[64:65], v[16:17]
	v_mov_b64_e32 v[48:49], v[16:17]
	v_mov_b64_e32 v[32:33], v[16:17]
	v_cmp_gt_u32_e64 s[0:1], 32, v85
	v_mov_b64_e32 v[62:63], v[14:15]
	v_mov_b64_e32 v[60:61], v[12:13]
	v_mov_b64_e32 v[58:59], v[10:11]
	v_mov_b64_e32 v[56:57], v[8:9]
	v_mov_b64_e32 v[54:55], v[6:7]
	v_mov_b64_e32 v[52:53], v[4:5]
	v_mov_b64_e32 v[50:51], v[2:3]
	v_mov_b64_e32 v[46:47], v[14:15]
	v_mov_b64_e32 v[44:45], v[12:13]
	v_mov_b64_e32 v[42:43], v[10:11]
	v_mov_b64_e32 v[40:41], v[8:9]
	v_mov_b64_e32 v[38:39], v[6:7]
	v_mov_b64_e32 v[36:37], v[4:5]
	v_mov_b64_e32 v[34:35], v[2:3]
	v_mov_b64_e32 v[30:31], v[14:15]
	v_mov_b64_e32 v[28:29], v[12:13]
	v_mov_b64_e32 v[26:27], v[10:11]
	v_mov_b64_e32 v[24:25], v[8:9]
	v_mov_b64_e32 v[22:23], v[6:7]
	v_mov_b64_e32 v[20:21], v[4:5]
	v_mov_b64_e32 v[18:19], v[2:3]
	s_waitcnt lgkmcnt(0)
	s_barrier
	s_add_u32 s80, s4, 0x4487c000
	s_addc_u32 s81, s5, 0
	s_add_u32 s82, s4, 0x4487e000
	s_addc_u32 s83, s5, 0
	s_add_u32 s84, s4, s97
	s_addc_u32 s85, s5, 0
	s_add_u32 s86, s4, 0x44880000
	s_addc_u32 s87, s5, 0
	s_add_u32 s88, s4, 0x44882000
	s_addc_u32 s89, s5, 0
	s_add_u32 s90, s4, s79
	s_addc_u32 s91, s5, 0
	v_exp_f32_e32 v126, v126
	v_exp_f32_e32 v127, v127
	v_exp_f32_e32 v124, v124
	v_exp_f32_e32 v125, v125
	v_exp_f32_e32 v122, v122
	v_exp_f32_e32 v123, v123
	v_exp_f32_e32 v118, v118
	v_exp_f32_e32 v119, v119
	v_exp_f32_e32 v116, v116
	v_exp_f32_e32 v117, v117
	v_exp_f32_e32 v128, v128
	v_exp_f32_e32 v129, v129
	v_exp_f32_e32 v120, v120
	v_exp_f32_e32 v121, v121
	v_exp_f32_e32 v114, v114
	v_exp_f32_e32 v115, v115
	v_mul_f32_e32 v226, 0xbf800000, v194
	v_add_f32_e32 v97, v134, v135
	v_add_f32_e32 v97, v136, v97
	v_add_f32_e32 v97, v138, v97
	v_add_f32_e32 v97, v155, v97
	v_add_f32_e32 v97, v156, v97
	v_add_f32_e32 v97, v137, v97
	v_add_f32_e32 v97, v154, v97
	v_add_f32_e32 v97, v131, v97
	v_add_f32_e32 v97, v133, v97
	v_add_f32_e32 v97, v139, v97
	v_add_f32_e32 v97, v152, v97
	v_add_f32_e32 v97, v132, v97
	v_add_f32_e32 v97, v140, v97
	v_add_f32_e32 v97, v141, v97
	v_add_f32_e32 v97, v153, v97
	v_add_f32_e32 v97, v126, v97
	v_add_f32_e32 v97, v127, v97
	v_add_f32_e32 v97, v124, v97
	v_add_f32_e32 v97, v125, v97
	v_add_f32_e32 v97, v122, v97
	v_add_f32_e32 v97, v123, v97
	v_add_f32_e32 v97, v118, v97
	v_add_f32_e32 v97, v119, v97
	v_add_f32_e32 v97, v116, v97
	v_add_f32_e32 v97, v117, v97
	v_add_f32_e32 v97, v128, v97
	v_add_f32_e32 v97, v129, v97
	v_add_f32_e32 v97, v120, v97
	v_add_f32_e32 v97, v121, v97
	v_add_f32_e32 v97, v114, v97
	v_add_f32_e32 v97, v115, v97
	v_cvt_pk_bf16_f32 v66, v134, v135
	v_cvt_pk_bf16_f32 v67, v136, v138
	v_cvt_pk_bf16_f32 v68, v155, v156
	v_cvt_pk_bf16_f32 v69, v137, v154
	v_cvt_pk_bf16_f32 v70, v131, v133
	v_cvt_pk_bf16_f32 v71, v139, v152
	v_cvt_pk_bf16_f32 v72, v132, v140
	v_cvt_pk_bf16_f32 v73, v141, v153
	v_cvt_pk_bf16_f32 v74, v126, v127
	v_cvt_pk_bf16_f32 v75, v124, v125
	v_cvt_pk_bf16_f32 v76, v122, v123
; #define SBAR() __builtin_amdgcn_sched_barrier(0)
; #define SLOAD(i, k0) do { sr_[i].vs0 = *reinterpret_cast<const bf16x8*>(&Vh[(long)((k0) + sr) * DV + sc]); sr_[i].vs1 = *reinterpret_cast<const bf16x8*>(&Vh[(long)((k0) + 32 + sr) * DV + sc]); \
;     _Pragma("unroll") for (int _c = 0; _c < NKC; ++_c) sr_[i].ks[_c] = *reinterpret_cast<const bf16x8*>(&Kh[(long)((k0) + krow[_c]) * DQK + kcol[_c]]); } while (0)
; #define SWRITE(b, i) do { *(LAS bf16x8*)(V_lds + (b) * SHM_V + vst0) = sr_[i].vs0; *(LAS bf16x8*)(V_lds + (b) * SHM_V + vst1) = sr_[i].vs1; \
;     _Pragma("unroll") for (int _c = 0; _c < NKC; ++_c) *(LAS bf16x8*)(K_lds + (b) * SHM_K + kswz<DQK>(krow[_c], kcol[_c] * 2)) = sr_[i].ks[_c]; } while (0)
; #define SWAIT() do { if constexpr (SDEPTH == 2) { if constexpr (NKC == 1) asm volatile("s_waitcnt vmcnt(3)" ::: "memory"); else if constexpr (NKC == 2) asm volatile("s_waitcnt vmcnt(4)" ::: "memory"); else asm volatile("s_waitcnt vmcnt(5)" ::: "memory"); } \
;     else asm volatile("s_waitcnt vmcnt(0)" ::: "memory"); } while (0)
; #define RESC(a) do { if (__any((a) < 1.f)) { if (hi == 0) al_l[r32] = (a); asm volatile("s_waitcnt lgkmcnt(0)" ::: "memory"); \
;     _Pragma("unroll") for (int d = 0; d < 4; ++d) _Pragma("unroll") for (int r = 0; r < 16; ++r) o[d][r] *= al_l[crow(r, hi)]; } } while (0)
; DI void finishSM(f32x16& p0, f32x16& p1, float alpha, float& l_reg, bf16x8& pa0, bf16x8& pa1, bf16x8& pa2, bf16x8& pa3) {
;     ...
;   PK4(p0, 0, pa0); PK4(p0, 8, pa1); PK4(p1, 0, pa2); PK4(p1, 8, pa3);
; template <int DQK, int SDEPTH, bool OUT_BF16, int QREG = DQK / 16, bool OUT_F16 = false> ...
;     ...
;   for (int j = 1; j + 1 < NT; j += 2) {
;     SBAR(); QKT(pB0, pB1, K_lds + SHM_K);
;     finishSM(pA0, pA1, alA, l_reg, pa0, pa1, pa2, pa3); SBAR();
;     SLOAD(SO, (j + SDEPTH) * KVBLK); SBAR();
;     pv_d0(o, vb0, pa0, pa1, pa2, pa3); partialSM(pB0, pB1, m_reg, mnB, alB, SCALE);
;     __syncthreads(); SWAIT(); SWRITE(0, SE);
;     RESC(alB); __syncthreads();
;     SBAR(); QKT(pA0, pA1, K_lds);
;     finishSM(pB0, pB1, alB, l_reg, pa0, pa1, pa2, pa3); SBAR();
;     if (SDEPTH == 1 || j + 3 < NT) SLOAD(SE, (j + 1 + SDEPTH) * KVBLK); SBAR();
;     pv_d0(o, vb0 + SHM_V, pa0, pa1, pa2, pa3); partialSM(pA0, pA1, m_reg, mnA, alA, SCALE);
	v_cvt_pk_bf16_f32 v77, v118, v119
	v_cvt_pk_bf16_f32 v78, v116, v117
	v_cvt_pk_bf16_f32 v79, v128, v129
	v_cvt_pk_bf16_f32 v80, v120, v121
	v_cvt_pk_bf16_f32 v81, v114, v115
	s_nop 1
	v_permlane32_swap_b32_e32 v66, v68
	v_permlane32_swap_b32_e32 v67, v69
	v_permlane32_swap_b32_e32 v70, v72
	v_permlane32_swap_b32_e32 v71, v73
	v_permlane32_swap_b32_e32 v74, v76
	v_permlane32_swap_b32_e32 v75, v77
	v_permlane32_swap_b32_e32 v78, v80
	v_permlane32_swap_b32_e32 v79, v81
	v_mov_b32_e32 v134, v66
	v_mov_b32_e32 v135, v67
	v_mov_b32_e32 v136, v68
	v_mov_b32_e32 v137, v69
	v_mov_b32_e32 v138, v70
	v_mov_b32_e32 v139, v71
	v_mov_b32_e32 v140, v72
	v_mov_b32_e32 v141, v73
	v_mov_b32_e32 v214, v74
	v_mov_b32_e32 v215, v75
	v_mov_b32_e32 v216, v76
	v_mov_b32_e32 v217, v77
	v_mov_b32_e32 v218, v78
	v_mov_b32_e32 v219, v79
	v_mov_b32_e32 v220, v80
	v_mov_b32_e32 v221, v81
	v_mov_b32_e32 v166, v97
	v_mov_b32_e32 v184, v226
	v_mov_b32_e32 v185, v226
	v_mov_b32_e32 v186, v226
	v_mov_b32_e32 v187, v226
	v_mov_b32_e32 v188, v226
	v_mov_b32_e32 v189, v226
	v_mov_b32_e32 v190, v226
	v_mov_b32_e32 v191, v226
	v_mov_b32_e32 v192, v226
	v_mov_b32_e32 v193, v226
	v_mov_b32_e32 v194, v226
	v_mov_b32_e32 v195, v226
	v_mov_b32_e32 v196, v226
	v_mov_b32_e32 v197, v226
	v_mov_b32_e32 v198, v226
	v_mov_b32_e32 v199, v226
	v_add_u32_e32 v172, 0x3000, v172
	v_add_u32_e32 v173, 0x3000, v173
	v_add_u32_e32 v174, 0x3000, v174
	v_add_u32_e32 v175, 0x3000, v175
	v_add_u32_e32 v176, 0x3000, v176
	v_add_u32_e32 v177, 0x3000, v177
	v_add_u32_e32 v178, 0x3000, v178
	v_add_u32_e32 v179, 0x3000, v179
	v_add_u32_e32 v180, 0x3000, v180
	v_add_u32_e32 v181, 0x3000, v181
	v_add_u32_e32 v182, 0x3000, v182
	v_add_u32_e32 v183, 0x3000, v183
.LBB0_748:
	global_load_dwordx4 v[114:117], v150, s[80:81]
	global_load_dwordx4 v[118:121], v150, s[82:83]
	global_load_dwordx4 v[122:125], v148, s[84:85]
	global_load_dwordx4 v[126:129], v146, s[84:85]
	global_load_dwordx4 v[130:133], v144, s[84:85]
	ds_read_b128 v[66:69], v172 offset:45056
	ds_read_b128 v[70:73], v172 offset:57344
	ds_read_b128 v[244:247], v173 offset:45056
	ds_read_b128 v[202:205], v173 offset:57344
	s_waitcnt lgkmcnt(3)
	v_mfma_f32_32x32x16_bf16 v[82:97], v[66:69], v[110:113], v[184:199]
	s_waitcnt lgkmcnt(2)
	v_mfma_f32_32x32x16_bf16 v[66:81], v[70:73], v[110:113], v[184:199]
	s_waitcnt lgkmcnt(1)
	v_mfma_f32_32x32x16_bf16 v[82:97], v[244:247], v[106:109], v[82:97]
	s_waitcnt lgkmcnt(0)
	v_mfma_f32_32x32x16_bf16 v[66:81], v[202:205], v[106:109], v[66:81]
	ds_read_b128 v[244:247], v174 offset:45056
	ds_read_b128 v[202:205], v174 offset:57344
	s_waitcnt lgkmcnt(1)
	v_mfma_f32_32x32x16_bf16 v[82:97], v[244:247], v[102:105], v[82:97]
	s_waitcnt lgkmcnt(0)
	v_mfma_f32_32x32x16_bf16 v[66:81], v[202:205], v[102:105], v[66:81]
	ds_read_b128 v[244:247], v175 offset:45056
	ds_read_b128 v[202:205], v175 offset:57344
	s_waitcnt lgkmcnt(1)
	v_mfma_f32_32x32x16_bf16 v[82:97], v[244:247], v[98:101], v[82:97]
	s_waitcnt lgkmcnt(0)
	v_mfma_f32_32x32x16_bf16 v[66:81], v[202:205], v[98:101], v[66:81]
	ds_read_b128 v[244:247], v176 offset:45056
	ds_read_b128 v[202:205], v176 offset:57344
	ds_read_b128 v[206:209], v162
	s_waitcnt lgkmcnt(0)
	v_mfma_f32_32x32x16_bf16 v[82:97], v[244:247], v[206:209], v[82:97]
	v_mfma_f32_32x32x16_bf16 v[66:81], v[202:205], v[206:209], v[66:81]
	ds_read_b128 v[244:247], v177 offset:45056
	ds_read_b128 v[202:205], v177 offset:57344
	ds_read_b128 v[206:209], v162 offset:1024
	s_waitcnt lgkmcnt(0)
	v_mfma_f32_32x32x16_bf16 v[82:97], v[244:247], v[206:209], v[82:97]
	v_mfma_f32_32x32x16_bf16 v[66:81], v[202:205], v[206:209], v[66:81]
	ds_read_b128 v[244:247], v178 offset:45056
	ds_read_b128 v[202:205], v178 offset:57344
	ds_read_b128 v[206:209], v162 offset:2048
	s_waitcnt lgkmcnt(0)
	v_mfma_f32_32x32x16_bf16 v[82:97], v[244:247], v[206:209], v[82:97]
	v_mfma_f32_32x32x16_bf16 v[66:81], v[202:205], v[206:209], v[66:81]
	ds_read_b128 v[244:247], v179 offset:45056
	ds_read_b128 v[202:205], v179 offset:57344
	ds_read_b128 v[206:209], v162 offset:3072
	s_waitcnt lgkmcnt(0)
	v_mfma_f32_32x32x16_bf16 v[82:97], v[244:247], v[206:209], v[82:97]
	v_mfma_f32_32x32x16_bf16 v[66:81], v[202:205], v[206:209], v[66:81]
	ds_read_b128 v[244:247], v180 offset:45056
	ds_read_b128 v[202:205], v180 offset:57344
	ds_read_b128 v[206:209], v162 offset:4096
	s_waitcnt lgkmcnt(0)
	v_mfma_f32_32x32x16_bf16 v[82:97], v[244:247], v[206:209], v[82:97]
	v_mfma_f32_32x32x16_bf16 v[66:81], v[202:205], v[206:209], v[66:81]
	ds_read_b128 v[244:247], v181 offset:45056
	ds_read_b128 v[202:205], v181 offset:57344
	ds_read_b128 v[206:209], v162 offset:5120
	s_waitcnt lgkmcnt(0)
	v_mfma_f32_32x32x16_bf16 v[82:97], v[244:247], v[206:209], v[82:97]
	v_mfma_f32_32x32x16_bf16 v[66:81], v[202:205], v[206:209], v[66:81]
	ds_read_b128 v[244:247], v182 offset:45056
	ds_read_b128 v[202:205], v182 offset:57344
	ds_read_b128 v[206:209], v162 offset:6144
	s_waitcnt lgkmcnt(0)
	v_mfma_f32_32x32x16_bf16 v[82:97], v[244:247], v[206:209], v[82:97]
	v_mfma_f32_32x32x16_bf16 v[66:81], v[202:205], v[206:209], v[66:81]
	ds_read_b128 v[244:247], v183 offset:45056
	ds_read_b128 v[202:205], v183 offset:57344
	ds_read_b128 v[206:209], v162 offset:7168
	s_waitcnt lgkmcnt(0)
	v_mfma_f32_32x32x16_bf16 v[82:97], v[244:247], v[206:209], v[82:97]
	v_mfma_f32_32x32x16_bf16 v[66:81], v[202:205], v[206:209], v[66:81]
	ds_read_b64_tr_b16 v[200:201], v163 offset:0x0
	ds_read_b64_tr_b16 v[202:203], v163 offset:0x800
	ds_read_b64_tr_b16 v[204:205], v163 offset:0x1000
	ds_read_b64_tr_b16 v[206:207], v163 offset:0x1800
	ds_read_b64_tr_b16 v[208:209], v163 offset:0x2000
	ds_read_b64_tr_b16 v[210:211], v163 offset:0x2800
	ds_read_b64_tr_b16 v[222:223], v163 offset:0x3000
	ds_read_b64_tr_b16 v[224:225], v163 offset:0x3800
	s_waitcnt lgkmcnt(0)
; #define SBAR() __builtin_amdgcn_sched_barrier(0)
; DI void finishSM(f32x16& p0, f32x16& p1, float alpha, float& l_reg, bf16x8& pa0, bf16x8& pa1, bf16x8& pa2, bf16x8& pa3) {
; #pragma unroll
;   for (int r = 0; r < 16; ++r) p1[r] = __builtin_amdgcn_exp2f(p1[r]);
;   float ps = 0;
; #pragma unroll
;   for (int r = 0; r < 16; ++r) ps += p0[r];
; #pragma unroll
;   for (int r = 0; r < 16; ++r) ps += p1[r];
;   { auto rr = __builtin_amdgcn_permlane32_swap(__float_as_uint(ps), __float_as_uint(ps), false, false);
;     ps = __uint_as_float(rr[0]) + __uint_as_float(rr[1]); }
;   l_reg = l_reg * alpha + ps;
;     ...
;   PK4(p0, 0, pa0); PK4(p0, 8, pa1); PK4(p1, 0, pa2); PK4(p1, 8, pa3);
; DI int v_st(int k, int c) { const int kk = (k & ~0xC) | ((k & 4) << 1) | ((k & 8) >> 1); return ((kk >> 3) * 4 + (c >> 5)) * 512 + ((kk & 7) * 32 + (c & 31)) * 2; }
; DI int v_rd_base(int lane) { return ((lane & 3) << 3) | (((lane >> 2) & 3) << 6) | (((lane >> 4) & 1) << 5) | (((lane >> 5) & 1) << 8); }
; template <int OFF> DI s16x4 tr_read(int vb) { s16x4 r; asm volatile("ds_read_b64_tr_b16 %0, %1 offset:%2" : "=&v"(r) : "v"(vb), "i"(OFF) : "memory"); return r; }
; template <int D0> DI void pv_one(f32x16& od, int vb, bf16x8 pa0, bf16x8 pa1, bf16x8 pa2, bf16x8 pa3) {
;   const s16x4 l0 = tr_read<v_rd_off(D0, 0, 0)>(vb), h0 = tr_read<v_rd_off(D0, 0, 1)>(vb), l1 = tr_read<v_rd_off(D0, 1, 0)>(vb), h1 = tr_read<v_rd_off(D0, 1, 1)>(vb);
;   const s16x4 l2 = tr_read<v_rd_off(D0, 2, 0)>(vb), h2 = tr_read<v_rd_off(D0, 2, 1)>(vb), l3 = tr_read<v_rd_off(D0, 3, 0)>(vb), h3 = tr_read<v_rd_off(D0, 3, 1)>(vb);
;   asm volatile("s_waitcnt lgkmcnt(0)" ::: "memory"); SBAR();
;     ...
;   od = __builtin_amdgcn_mfma_f32_32x32x16_bf16(pa0, PK(l0, h0), od, 0, 0, 0);
;   od = __builtin_amdgcn_mfma_f32_32x32x16_bf16(pa1, PK(l1, h1), od, 0, 0, 0);
;   od = __builtin_amdgcn_mfma_f32_32x32x16_bf16(pa2, PK(l2, h2), od, 0, 0, 0);
;   od = __builtin_amdgcn_mfma_f32_32x32x16_bf16(pa3, PK(l3, h3), od, 0, 0, 0);
;     ...
; }
; DI void pv_d0(f32x16* o, int vb, bf16x8 pa0, bf16x8 pa1, bf16x8 pa2, bf16x8 pa3) {
;   pv_one<0>(o[0], vb, pa0, pa1, pa2, pa3); pv_one<1>(o[1], vb, pa0, pa1, pa2, pa3); pv_one<2>(o[2], vb, pa0, pa1, pa2, pa3); pv_one<3>(o[3], vb, pa0, pa1, pa2, pa3);
; }
	v_mfma_f32_32x32x16_bf16 v[2:17], v[134:137], v[200:203], v[2:17]
	ds_read_b64_tr_b16 v[200:201], v163 offset:0x200
	ds_read_b64_tr_b16 v[202:203], v163 offset:0xa00
	v_exp_f32_e32 v82, v82
	v_exp_f32_e32 v83, v83
	v_exp_f32_e32 v84, v84
	v_exp_f32_e32 v85, v85
	v_exp_f32_e32 v86, v86
	v_add_f32_e32 v252, v82, v83
	v_mfma_f32_32x32x16_bf16 v[2:17], v[138:141], v[204:207], v[2:17]
	ds_read_b64_tr_b16 v[204:205], v163 offset:0x1200
	ds_read_b64_tr_b16 v[206:207], v163 offset:0x1a00
	v_exp_f32_e32 v87, v87
	v_add_f32_e32 v252, v84, v252
	v_exp_f32_e32 v88, v88
	v_add_f32_e32 v252, v85, v252
	v_cvt_pk_bf16_f32 v152, v82, v83
	v_mfma_f32_32x32x16_bf16 v[2:17], v[214:217], v[208:211], v[2:17]
	ds_read_b64_tr_b16 v[208:209], v163 offset:0x2200
	ds_read_b64_tr_b16 v[210:211], v163 offset:0x2a00
	v_exp_f32_e32 v89, v89
	v_add_f32_e32 v252, v86, v252
	v_exp_f32_e32 v90, v90
	v_add_f32_e32 v252, v87, v252
	v_cvt_pk_bf16_f32 v153, v84, v85
	v_exp_f32_e32 v91, v91
	v_mfma_f32_32x32x16_bf16 v[2:17], v[218:221], v[222:225], v[2:17]
	ds_read_b64_tr_b16 v[222:223], v163 offset:0x3200
	ds_read_b64_tr_b16 v[224:225], v163 offset:0x3a00
	v_add_f32_e32 v252, v88, v252
	v_exp_f32_e32 v92, v92
	v_add_f32_e32 v252, v89, v252
	v_cvt_pk_bf16_f32 v154, v86, v87
	v_exp_f32_e32 v93, v93
	s_waitcnt lgkmcnt(0)
	v_mfma_f32_32x32x16_bf16 v[50:65], v[134:137], v[200:203], v[50:65]
	ds_read_b64_tr_b16 v[200:201], v163 offset:0x400
	ds_read_b64_tr_b16 v[202:203], v163 offset:0xc00
	v_add_f32_e32 v252, v90, v252
	v_exp_f32_e32 v94, v94
	v_add_f32_e32 v252, v91, v252
	v_cvt_pk_bf16_f32 v155, v88, v89
	v_exp_f32_e32 v95, v95
	v_add_f32_e32 v252, v92, v252
	v_mfma_f32_32x32x16_bf16 v[50:65], v[138:141], v[204:207], v[50:65]
	ds_read_b64_tr_b16 v[204:205], v163 offset:0x1400
	ds_read_b64_tr_b16 v[206:207], v163 offset:0x1c00
	v_exp_f32_e32 v96, v96
	v_add_f32_e32 v252, v93, v252
	v_cvt_pk_bf16_f32 v156, v90, v91
	v_exp_f32_e32 v97, v97
	v_add_f32_e32 v252, v94, v252
	v_mfma_f32_32x32x16_bf16 v[50:65], v[214:217], v[208:211], v[50:65]
	ds_read_b64_tr_b16 v[208:209], v163 offset:0x2400
	ds_read_b64_tr_b16 v[210:211], v163 offset:0x2c00
	v_exp_f32_e32 v66, v66
	v_add_f32_e32 v252, v95, v252
	v_cvt_pk_bf16_f32 v157, v92, v93
	v_permlane32_swap_b32_e32 v152, v154
	v_exp_f32_e32 v67, v67
	v_add_f32_e32 v252, v96, v252
	v_mfma_f32_32x32x16_bf16 v[50:65], v[218:221], v[222:225], v[50:65]
	ds_read_b64_tr_b16 v[222:223], v163 offset:0x3400
	ds_read_b64_tr_b16 v[224:225], v163 offset:0x3c00
	v_permlane32_swap_b32_e32 v153, v155
	v_exp_f32_e32 v68, v68
	v_add_f32_e32 v252, v97, v252
	v_cvt_pk_bf16_f32 v158, v94, v95
	v_exp_f32_e32 v69, v69
	s_waitcnt lgkmcnt(0)
	v_mfma_f32_32x32x16_bf16 v[34:49], v[134:137], v[200:203], v[34:49]
	ds_read_b64_tr_b16 v[200:201], v163 offset:0x600
	ds_read_b64_tr_b16 v[202:203], v163 offset:0xe00
	v_add_f32_e32 v252, v66, v252
	v_exp_f32_e32 v70, v70
	v_add_f32_e32 v252, v67, v252
	v_cvt_pk_bf16_f32 v159, v96, v97
	v_exp_f32_e32 v71, v71
	v_add_f32_e32 v252, v68, v252
	v_mfma_f32_32x32x16_bf16 v[34:49], v[138:141], v[204:207], v[34:49]
	ds_read_b64_tr_b16 v[204:205], v163 offset:0x1600
	ds_read_b64_tr_b16 v[206:207], v163 offset:0x1e00
	v_exp_f32_e32 v72, v72
	v_add_f32_e32 v252, v69, v252
	v_cvt_pk_bf16_f32 v228, v66, v67
	v_exp_f32_e32 v73, v73
	v_add_f32_e32 v252, v70, v252
	v_exp_f32_e32 v74, v74
	v_mfma_f32_32x32x16_bf16 v[34:49], v[214:217], v[208:211], v[34:49]
	ds_read_b64_tr_b16 v[208:209], v163 offset:0x2600
	ds_read_b64_tr_b16 v[210:211], v163 offset:0x2e00
	v_add_f32_e32 v252, v71, v252
	v_cvt_pk_bf16_f32 v229, v68, v69
	v_permlane32_swap_b32_e32 v156, v158
	v_exp_f32_e32 v75, v75
	v_add_f32_e32 v252, v72, v252
	v_mfma_f32_32x32x16_bf16 v[34:49], v[218:221], v[222:225], v[34:49]
	ds_read_b64_tr_b16 v[222:223], v163 offset:0x3600
	ds_read_b64_tr_b16 v[224:225], v163 offset:0x3e00
	v_permlane32_swap_b32_e32 v157, v159
	v_exp_f32_e32 v76, v76
	v_add_f32_e32 v252, v73, v252
	v_cvt_pk_bf16_f32 v230, v70, v71
	v_exp_f32_e32 v77, v77
	v_add_f32_e32 v252, v74, v252
	s_waitcnt lgkmcnt(0)
	v_mfma_f32_32x32x16_bf16 v[18:33], v[134:137], v[200:203], v[18:33]
	v_exp_f32_e32 v78, v78
	v_add_f32_e32 v252, v75, v252
	v_cvt_pk_bf16_f32 v231, v72, v73
	v_exp_f32_e32 v79, v79
	v_add_f32_e32 v252, v76, v252
	v_mfma_f32_32x32x16_bf16 v[18:33], v[138:141], v[204:207], v[18:33]
	v_exp_f32_e32 v80, v80
	v_add_f32_e32 v252, v77, v252
	v_cvt_pk_bf16_f32 v248, v74, v75
	v_exp_f32_e32 v81, v81
	v_add_f32_e32 v252, v78, v252
	v_add_f32_e32 v252, v79, v252
	v_mfma_f32_32x32x16_bf16 v[18:33], v[214:217], v[208:211], v[18:33]
	v_cvt_pk_bf16_f32 v249, v76, v77
	v_permlane32_swap_b32_e32 v228, v230
	v_add_f32_e32 v252, v80, v252
	v_permlane32_swap_b32_e32 v229, v231
	v_add_f32_e32 v252, v81, v252
	v_mfma_f32_32x32x16_bf16 v[18:33], v[218:221], v[222:225], v[18:33]
	v_cvt_pk_bf16_f32 v250, v78, v79
	v_cvt_pk_bf16_f32 v251, v80, v81
	v_cmp_nge_f32_e32 vcc, 0x453a4f54, v252
	v_add_f32_e32 v227, v166, v252
	v_permlane32_swap_b32_e32 v248, v250
	v_permlane32_swap_b32_e32 v249, v251
	s_barrier
	s_waitcnt vmcnt(0)
	ds_write_b128 v167, v[114:117]
	ds_write_b128 v168, v[118:121]
	ds_write_b128 v169, v[122:125] offset:32768
	ds_write_b128 v170, v[126:129] offset:32768
	ds_write_b128 v171, v[130:133] offset:32768
	s_cbranch_vccz .LBB0_752
; DI void partialSM(f32x16& p0, f32x16& p1, float& m_reg, float& mn, float& alpha, const float SCALE) {
;   const float C = SCALE * 1.4426950408889634f;
;   float pmax = p0[0];
; #pragma unroll
;   for (int r = 1; r < 16; ++r) pmax = fmaxf(pmax, p0[r]);
; #pragma unroll
;   for (int r = 0; r < 16; ++r) pmax = fmaxf(pmax, p1[r]);
;   { auto rr = __builtin_amdgcn_permlane32_swap(__float_as_uint(pmax), __float_as_uint(pmax), false, false);
;     pmax = fmaxf(__uint_as_float(rr[0]), __uint_as_float(rr[1])); }
;   if (__builtin_expect(__all(pmax - m_reg <= THR / SCALE), 1)) { mn = m_reg; alpha = 1.f; }
;   else { mn = fmaxf(m_reg, pmax); alpha = __builtin_amdgcn_exp2f((m_reg - mn) * C); m_reg = mn; }
;   const float mnC = -mn * C;
; #pragma unroll
;   for (int r = 0; r < 16; ++r) p0[r] = fmaf(p0[r], C, mnC);
; #pragma unroll
;   for (int r = 0; r < 16; ++r) p1[r] = fmaf(p1[r], C, mnC);
; #pragma unroll
;   for (int r = 0; r < 16; ++r) p0[r] = __builtin_amdgcn_exp2f(p0[r]);
; }
	ds_read_b128 v[66:69], v172 offset:45056
	ds_read_b128 v[70:73], v172 offset:57344
	ds_read_b128 v[244:247], v173 offset:45056
	ds_read_b128 v[202:205], v173 offset:57344
	s_waitcnt lgkmcnt(3)
	v_mfma_f32_32x32x16_bf16 v[82:97], v[66:69], v[110:113], 0
	s_waitcnt lgkmcnt(2)
	v_mfma_f32_32x32x16_bf16 v[66:81], v[70:73], v[110:113], 0
	s_waitcnt lgkmcnt(1)
	v_mfma_f32_32x32x16_bf16 v[82:97], v[244:247], v[106:109], v[82:97]
	s_waitcnt lgkmcnt(0)
	v_mfma_f32_32x32x16_bf16 v[66:81], v[202:205], v[106:109], v[66:81]
	ds_read_b128 v[244:247], v174 offset:45056
	ds_read_b128 v[202:205], v174 offset:57344
	s_waitcnt lgkmcnt(1)
	v_mfma_f32_32x32x16_bf16 v[82:97], v[244:247], v[102:105], v[82:97]
	s_waitcnt lgkmcnt(0)
	v_mfma_f32_32x32x16_bf16 v[66:81], v[202:205], v[102:105], v[66:81]
	ds_read_b128 v[244:247], v175 offset:45056
	ds_read_b128 v[202:205], v175 offset:57344
	s_waitcnt lgkmcnt(1)
	v_mfma_f32_32x32x16_bf16 v[82:97], v[244:247], v[98:101], v[82:97]
	s_waitcnt lgkmcnt(0)
	v_mfma_f32_32x32x16_bf16 v[66:81], v[202:205], v[98:101], v[66:81]
	ds_read_b128 v[244:247], v176 offset:45056
	ds_read_b128 v[202:205], v176 offset:57344
	ds_read_b128 v[206:209], v162
	s_waitcnt lgkmcnt(0)
	v_mfma_f32_32x32x16_bf16 v[82:97], v[244:247], v[206:209], v[82:97]
	v_mfma_f32_32x32x16_bf16 v[66:81], v[202:205], v[206:209], v[66:81]
	ds_read_b128 v[244:247], v177 offset:45056
	ds_read_b128 v[202:205], v177 offset:57344
	ds_read_b128 v[206:209], v162 offset:1024
	s_waitcnt lgkmcnt(0)
	v_mfma_f32_32x32x16_bf16 v[82:97], v[244:247], v[206:209], v[82:97]
	v_mfma_f32_32x32x16_bf16 v[66:81], v[202:205], v[206:209], v[66:81]
	ds_read_b128 v[244:247], v178 offset:45056
	ds_read_b128 v[202:205], v178 offset:57344
	ds_read_b128 v[206:209], v162 offset:2048
	s_waitcnt lgkmcnt(0)
	v_mfma_f32_32x32x16_bf16 v[82:97], v[244:247], v[206:209], v[82:97]
	v_mfma_f32_32x32x16_bf16 v[66:81], v[202:205], v[206:209], v[66:81]
	ds_read_b128 v[244:247], v179 offset:45056
	ds_read_b128 v[202:205], v179 offset:57344
	ds_read_b128 v[206:209], v162 offset:3072
	s_waitcnt lgkmcnt(0)
	v_mfma_f32_32x32x16_bf16 v[82:97], v[244:247], v[206:209], v[82:97]
	v_mfma_f32_32x32x16_bf16 v[66:81], v[202:205], v[206:209], v[66:81]
	ds_read_b128 v[244:247], v180 offset:45056
	ds_read_b128 v[202:205], v180 offset:57344
	ds_read_b128 v[206:209], v162 offset:4096
	s_waitcnt lgkmcnt(0)
	v_mfma_f32_32x32x16_bf16 v[82:97], v[244:247], v[206:209], v[82:97]
	v_mfma_f32_32x32x16_bf16 v[66:81], v[202:205], v[206:209], v[66:81]
	ds_read_b128 v[244:247], v181 offset:45056
	ds_read_b128 v[202:205], v181 offset:57344
	ds_read_b128 v[206:209], v162 offset:5120
	s_waitcnt lgkmcnt(0)
	v_mfma_f32_32x32x16_bf16 v[82:97], v[244:247], v[206:209], v[82:97]
	v_mfma_f32_32x32x16_bf16 v[66:81], v[202:205], v[206:209], v[66:81]
	ds_read_b128 v[244:247], v182 offset:45056
	ds_read_b128 v[202:205], v182 offset:57344
	ds_read_b128 v[206:209], v162 offset:6144
	s_waitcnt lgkmcnt(0)
	v_mfma_f32_32x32x16_bf16 v[82:97], v[244:247], v[206:209], v[82:97]
	v_mfma_f32_32x32x16_bf16 v[66:81], v[202:205], v[206:209], v[66:81]
	ds_read_b128 v[244:247], v183 offset:45056
	ds_read_b128 v[202:205], v183 offset:57344
	ds_read_b128 v[206:209], v162 offset:7168
	s_waitcnt lgkmcnt(0)
	v_mfma_f32_32x32x16_bf16 v[82:97], v[244:247], v[206:209], v[82:97]
	v_mfma_f32_32x32x16_bf16 v[66:81], v[202:205], v[206:209], v[66:81]
	s_nop 7
	s_nop 7
	v_max3_f32 v131, v82, v83, v84
	v_max3_f32 v132, v85, v86, v87
	v_max3_f32 v131, v131, v88, v89
	v_max3_f32 v132, v132, v90, v91
	v_max3_f32 v131, v131, v92, v93
	v_max3_f32 v132, v132, v94, v95
	v_max3_f32 v131, v131, v96, v97
	v_max3_f32 v132, v132, v66, v67
	v_max3_f32 v131, v131, v68, v69
	v_max3_f32 v132, v132, v70, v71
	v_max3_f32 v131, v131, v72, v73
	v_max3_f32 v132, v132, v74, v75
	v_max3_f32 v131, v131, v76, v77
	v_max3_f32 v132, v132, v78, v79
	v_max3_f32 v131, v131, v80, v81
	v_max_f32_e32 v131, v131, v132
	v_mov_b32_e32 v132, v131
	s_nop 1
	v_permlane32_swap_b32_e32 v131, v132
	v_max_f32_e32 v131, v131, v132
	v_max_f32_e64 v131, -v226, v131
	v_sub_f32_e64 v132, -v226, v131
	v_exp_f32_e32 v200, v132
	v_mul_f32_e32 v226, 0xbf800000, v131
	v_mov_b32_e32 v184, v226
	v_mov_b32_e32 v185, v226
	v_mov_b32_e32 v186, v226
	v_mov_b32_e32 v187, v226
	v_mov_b32_e32 v188, v226
	v_mov_b32_e32 v189, v226
	v_mov_b32_e32 v190, v226
	v_mov_b32_e32 v191, v226
	v_mov_b32_e32 v192, v226
	v_mov_b32_e32 v193, v226
	v_mov_b32_e32 v194, v226
	v_mov_b32_e32 v195, v226
	v_mov_b32_e32 v196, v226
	v_mov_b32_e32 v197, v226
	v_mov_b32_e32 v198, v226
	v_mov_b32_e32 v199, v226
	v_add_f32_e32 v82, v226, v82
	v_add_f32_e32 v83, v226, v83
	v_add_f32_e32 v84, v226, v84
	v_add_f32_e32 v85, v226, v85
	v_add_f32_e32 v86, v226, v86
	v_add_f32_e32 v87, v226, v87
	v_add_f32_e32 v88, v226, v88
	v_add_f32_e32 v89, v226, v89
	v_add_f32_e32 v90, v226, v90
	v_add_f32_e32 v91, v226, v91
	v_add_f32_e32 v92, v226, v92
	v_add_f32_e32 v93, v226, v93
	v_add_f32_e32 v94, v226, v94
	v_add_f32_e32 v95, v226, v95
	v_add_f32_e32 v96, v226, v96
	v_add_f32_e32 v97, v226, v97
	v_add_f32_e32 v66, v226, v66
	v_add_f32_e32 v67, v226, v67
	v_add_f32_e32 v68, v226, v68
	v_add_f32_e32 v69, v226, v69
	v_add_f32_e32 v70, v226, v70
	v_add_f32_e32 v71, v226, v71
	v_add_f32_e32 v72, v226, v72
	v_add_f32_e32 v73, v226, v73
	v_add_f32_e32 v74, v226, v74
	v_add_f32_e32 v75, v226, v75
	v_add_f32_e32 v76, v226, v76
	v_add_f32_e32 v77, v226, v77
	v_add_f32_e32 v78, v226, v78
	v_add_f32_e32 v79, v226, v79
	v_add_f32_e32 v80, v226, v80
	v_add_f32_e32 v81, v226, v81
	v_exp_f32_e32 v82, v82
	v_exp_f32_e32 v83, v83
	v_exp_f32_e32 v84, v84
	v_exp_f32_e32 v85, v85
	v_exp_f32_e32 v86, v86
; DI void finishSM(f32x16& p0, f32x16& p1, float alpha, float& l_reg, bf16x8& pa0, bf16x8& pa1, bf16x8& pa2, bf16x8& pa3) {
; #pragma unroll
;   for (int r = 0; r < 16; ++r) p1[r] = __builtin_amdgcn_exp2f(p1[r]);
;   float ps = 0;
; #pragma unroll
;   for (int r = 0; r < 16; ++r) ps += p0[r];
; #pragma unroll
;   for (int r = 0; r < 16; ++r) ps += p1[r];
;   { auto rr = __builtin_amdgcn_permlane32_swap(__float_as_uint(ps), __float_as_uint(ps), false, false);
;     ps = __uint_as_float(rr[0]) + __uint_as_float(rr[1]); }
;   l_reg = l_reg * alpha + ps;
;     ...
;   PK4(p0, 0, pa0); PK4(p0, 8, pa1); PK4(p1, 0, pa2); PK4(p1, 8, pa3);
	v_exp_f32_e32 v87, v87
	v_exp_f32_e32 v88, v88
	v_exp_f32_e32 v89, v89
	v_exp_f32_e32 v90, v90
	v_exp_f32_e32 v91, v91
	v_exp_f32_e32 v92, v92
	v_exp_f32_e32 v93, v93
	v_exp_f32_e32 v94, v94
	v_exp_f32_e32 v95, v95
	v_exp_f32_e32 v96, v96
	v_exp_f32_e32 v97, v97
	v_exp_f32_e32 v66, v66
	v_exp_f32_e32 v67, v67
	v_exp_f32_e32 v68, v68
	v_exp_f32_e32 v69, v69
	v_exp_f32_e32 v70, v70
	v_exp_f32_e32 v71, v71
	v_exp_f32_e32 v72, v72
	v_exp_f32_e32 v73, v73
	v_exp_f32_e32 v74, v74
	v_exp_f32_e32 v75, v75
	v_exp_f32_e32 v76, v76
	v_exp_f32_e32 v77, v77
	v_exp_f32_e32 v78, v78
	v_exp_f32_e32 v79, v79
	v_exp_f32_e32 v80, v80
	v_exp_f32_e32 v81, v81
	s_nop 0
	v_add_f32_e32 v252, v82, v83
	v_add_f32_e32 v252, v84, v252
	v_add_f32_e32 v252, v85, v252
	v_add_f32_e32 v252, v86, v252
	v_add_f32_e32 v252, v87, v252
	v_add_f32_e32 v252, v88, v252
	v_add_f32_e32 v252, v89, v252
	v_add_f32_e32 v252, v90, v252
	v_add_f32_e32 v252, v91, v252
	v_add_f32_e32 v252, v92, v252
	v_add_f32_e32 v252, v93, v252
	v_add_f32_e32 v252, v94, v252
	v_add_f32_e32 v252, v95, v252
	v_add_f32_e32 v252, v96, v252
	v_add_f32_e32 v252, v97, v252
	v_add_f32_e32 v252, v66, v252
	v_add_f32_e32 v252, v67, v252
	v_add_f32_e32 v252, v68, v252
	v_add_f32_e32 v252, v69, v252
	v_add_f32_e32 v252, v70, v252
	v_add_f32_e32 v252, v71, v252
	v_add_f32_e32 v252, v72, v252
	v_add_f32_e32 v252, v73, v252
	v_add_f32_e32 v252, v74, v252
	v_add_f32_e32 v252, v75, v252
	v_add_f32_e32 v252, v76, v252
	v_add_f32_e32 v252, v77, v252
	v_add_f32_e32 v252, v78, v252
	v_add_f32_e32 v252, v79, v252
	v_add_f32_e32 v252, v80, v252
	v_add_f32_e32 v252, v81, v252
	v_fma_f32 v227, v200, v166, v252
	v_cvt_pk_bf16_f32 v152, v82, v83
	v_cvt_pk_bf16_f32 v153, v84, v85
	v_cvt_pk_bf16_f32 v154, v86, v87
	v_cvt_pk_bf16_f32 v155, v88, v89
	v_cvt_pk_bf16_f32 v156, v90, v91
	v_cvt_pk_bf16_f32 v157, v92, v93
	v_cvt_pk_bf16_f32 v158, v94, v95
	v_cvt_pk_bf16_f32 v159, v96, v97
	v_cvt_pk_bf16_f32 v228, v66, v67
	v_cvt_pk_bf16_f32 v229, v68, v69
	v_cvt_pk_bf16_f32 v230, v70, v71
	v_cvt_pk_bf16_f32 v231, v72, v73
	v_cvt_pk_bf16_f32 v248, v74, v75
	v_cvt_pk_bf16_f32 v249, v76, v77
	v_cvt_pk_bf16_f32 v250, v78, v79
	v_cvt_pk_bf16_f32 v251, v80, v81
	s_nop 1
	v_permlane32_swap_b32_e32 v152, v154
	v_permlane32_swap_b32_e32 v153, v155
	v_permlane32_swap_b32_e32 v156, v158
	v_permlane32_swap_b32_e32 v157, v159
	v_permlane32_swap_b32_e32 v228, v230
	v_permlane32_swap_b32_e32 v229, v231
	v_permlane32_swap_b32_e32 v248, v250
	v_permlane32_swap_b32_e32 v249, v251
	s_and_saveexec_b64 s[10:11], s[0:1]
	ds_write_b32 v164, v200 offset:128
	s_or_b64 exec, exec, s[10:11]
	s_waitcnt lgkmcnt(0)
	v_add_u32_e32 v126, v143, v0
	ds_read_b128 v[114:117], v126 offset:224
	ds_read_b128 v[118:121], v126 offset:192
	ds_read_b128 v[122:125], v126 offset:160
	ds_read_b128 v[126:129], v126 offset:128
	s_waitcnt lgkmcnt(3)
	v_pk_mul_f32 v[14:15], v[14:15], v[114:115]
	s_waitcnt lgkmcnt(2)
	v_pk_mul_f32 v[10:11], v[10:11], v[118:119]
	s_waitcnt lgkmcnt(1)
	v_pk_mul_f32 v[6:7], v[6:7], v[122:123]
	v_pk_mul_f32 v[16:17], v[16:17], v[116:117]
	v_pk_mul_f32 v[12:13], v[12:13], v[120:121]
	v_pk_mul_f32 v[8:9], v[8:9], v[124:125]
	s_waitcnt lgkmcnt(0)
	v_pk_mul_f32 v[4:5], v[4:5], v[128:129]
	v_pk_mul_f32 v[2:3], v[2:3], v[126:127]
	v_pk_mul_f32 v[62:63], v[62:63], v[114:115]
	v_pk_mul_f32 v[58:59], v[58:59], v[118:119]
	v_pk_mul_f32 v[54:55], v[54:55], v[122:123]
	v_pk_mul_f32 v[64:65], v[64:65], v[116:117]
	v_pk_mul_f32 v[60:61], v[60:61], v[120:121]
	v_pk_mul_f32 v[56:57], v[56:57], v[124:125]
	v_pk_mul_f32 v[52:53], v[52:53], v[128:129]
	v_pk_mul_f32 v[50:51], v[50:51], v[126:127]
	v_pk_mul_f32 v[46:47], v[46:47], v[114:115]
	v_pk_mul_f32 v[42:43], v[42:43], v[118:119]
	v_pk_mul_f32 v[38:39], v[38:39], v[122:123]
	v_pk_mul_f32 v[48:49], v[48:49], v[116:117]
	v_pk_mul_f32 v[44:45], v[44:45], v[120:121]
	v_pk_mul_f32 v[40:41], v[40:41], v[124:125]
	v_pk_mul_f32 v[36:37], v[36:37], v[128:129]
	v_pk_mul_f32 v[34:35], v[34:35], v[126:127]
	v_pk_mul_f32 v[30:31], v[30:31], v[114:115]
	v_pk_mul_f32 v[26:27], v[26:27], v[118:119]
	v_pk_mul_f32 v[22:23], v[22:23], v[122:123]
	v_pk_mul_f32 v[32:33], v[32:33], v[116:117]
	v_pk_mul_f32 v[28:29], v[28:29], v[120:121]
	v_pk_mul_f32 v[24:25], v[24:25], v[124:125]
	v_pk_mul_f32 v[20:21], v[20:21], v[128:129]
	v_pk_mul_f32 v[18:19], v[18:19], v[126:127]
; #define SBAR() __builtin_amdgcn_sched_barrier(0)
; #define SLOAD(i, k0) do { sr_[i].vs0 = *reinterpret_cast<const bf16x8*>(&Vh[(long)((k0) + sr) * DV + sc]); sr_[i].vs1 = *reinterpret_cast<const bf16x8*>(&Vh[(long)((k0) + 32 + sr) * DV + sc]); \
;     _Pragma("unroll") for (int _c = 0; _c < NKC; ++_c) sr_[i].ks[_c] = *reinterpret_cast<const bf16x8*>(&Kh[(long)((k0) + krow[_c]) * DQK + kcol[_c]]); } while (0)
; DI int v_st(int k, int c) { const int kk = (k & ~0xC) | ((k & 4) << 1) | ((k & 8) >> 1); return ((kk >> 3) * 4 + (c >> 5)) * 512 + ((kk & 7) * 32 + (c & 31)) * 2; }
; DI int v_rd_base(int lane) { return ((lane & 3) << 3) | (((lane >> 2) & 3) << 6) | (((lane >> 4) & 1) << 5) | (((lane >> 5) & 1) << 8); }
; template <int OFF> DI s16x4 tr_read(int vb) { s16x4 r; asm volatile("ds_read_b64_tr_b16 %0, %1 offset:%2" : "=&v"(r) : "v"(vb), "i"(OFF) : "memory"); return r; }
; template <int D0> DI void pv_one(f32x16& od, int vb, bf16x8 pa0, bf16x8 pa1, bf16x8 pa2, bf16x8 pa3) {
;   const s16x4 l0 = tr_read<v_rd_off(D0, 0, 0)>(vb), h0 = tr_read<v_rd_off(D0, 0, 1)>(vb), l1 = tr_read<v_rd_off(D0, 1, 0)>(vb), h1 = tr_read<v_rd_off(D0, 1, 1)>(vb);
;   const s16x4 l2 = tr_read<v_rd_off(D0, 2, 0)>(vb), h2 = tr_read<v_rd_off(D0, 2, 1)>(vb), l3 = tr_read<v_rd_off(D0, 3, 0)>(vb), h3 = tr_read<v_rd_off(D0, 3, 1)>(vb);
;   asm volatile("s_waitcnt lgkmcnt(0)" ::: "memory"); SBAR();
;     ...
;   od = __builtin_amdgcn_mfma_f32_32x32x16_bf16(pa0, PK(l0, h0), od, 0, 0, 0);
;   od = __builtin_amdgcn_mfma_f32_32x32x16_bf16(pa1, PK(l1, h1), od, 0, 0, 0);
;   od = __builtin_amdgcn_mfma_f32_32x32x16_bf16(pa2, PK(l2, h2), od, 0, 0, 0);
;   od = __builtin_amdgcn_mfma_f32_32x32x16_bf16(pa3, PK(l3, h3), od, 0, 0, 0);
;     ...
; }
; DI void pv_d0(f32x16* o, int vb, bf16x8 pa0, bf16x8 pa1, bf16x8 pa2, bf16x8 pa3) {
;   pv_one<0>(o[0], vb, pa0, pa1, pa2, pa3); pv_one<1>(o[1], vb, pa0, pa1, pa2, pa3); pv_one<2>(o[2], vb, pa0, pa1, pa2, pa3); pv_one<3>(o[3], vb, pa0, pa1, pa2, pa3);
; }
; template <int DQK, int SDEPTH, bool OUT_BF16, int QREG = DQK / 16, bool OUT_F16 = false> ...
;     ...
;     SBAR(); QKT(pA0, pA1, K_lds);
;     finishSM(pB0, pB1, alB, l_reg, pa0, pa1, pa2, pa3); SBAR();
;     if (SDEPTH == 1 || j + 3 < NT) SLOAD(SE, (j + 1 + SDEPTH) * KVBLK); SBAR();
;     pv_d0(o, vb0 + SHM_V, pa0, pa1, pa2, pa3); partialSM(pA0, pA1, m_reg, mnA, alA, SCALE);
.LBB0_752:
	s_waitcnt lgkmcnt(0)
	s_barrier
	global_load_dwordx4 v[114:117], v150, s[86:87]
	global_load_dwordx4 v[118:121], v150, s[88:89]
	global_load_dwordx4 v[122:125], v148, s[90:91]
	global_load_dwordx4 v[126:129], v146, s[90:91]
	global_load_dwordx4 v[130:133], v144, s[90:91]
	ds_read_b128 v[66:69], v172 offset:20480
	ds_read_b128 v[70:73], v172 offset:32768
	ds_read_b128 v[244:247], v173 offset:20480
	ds_read_b128 v[202:205], v173 offset:32768
	s_waitcnt lgkmcnt(3)
	v_mfma_f32_32x32x16_bf16 v[82:97], v[66:69], v[110:113], v[184:199]
	s_waitcnt lgkmcnt(2)
	v_mfma_f32_32x32x16_bf16 v[66:81], v[70:73], v[110:113], v[184:199]
	s_waitcnt lgkmcnt(1)
	v_mfma_f32_32x32x16_bf16 v[82:97], v[244:247], v[106:109], v[82:97]
	s_waitcnt lgkmcnt(0)
	v_mfma_f32_32x32x16_bf16 v[66:81], v[202:205], v[106:109], v[66:81]
	ds_read_b128 v[244:247], v174 offset:20480
	ds_read_b128 v[202:205], v174 offset:32768
	s_waitcnt lgkmcnt(1)
	v_mfma_f32_32x32x16_bf16 v[82:97], v[244:247], v[102:105], v[82:97]
	s_waitcnt lgkmcnt(0)
	v_mfma_f32_32x32x16_bf16 v[66:81], v[202:205], v[102:105], v[66:81]
	ds_read_b128 v[244:247], v175 offset:20480
	ds_read_b128 v[202:205], v175 offset:32768
	s_waitcnt lgkmcnt(1)
	v_mfma_f32_32x32x16_bf16 v[82:97], v[244:247], v[98:101], v[82:97]
	s_waitcnt lgkmcnt(0)
	v_mfma_f32_32x32x16_bf16 v[66:81], v[202:205], v[98:101], v[66:81]
	ds_read_b128 v[244:247], v176 offset:20480
	ds_read_b128 v[202:205], v176 offset:32768
	ds_read_b128 v[206:209], v162
	s_waitcnt lgkmcnt(0)
	v_mfma_f32_32x32x16_bf16 v[82:97], v[244:247], v[206:209], v[82:97]
	v_mfma_f32_32x32x16_bf16 v[66:81], v[202:205], v[206:209], v[66:81]
	ds_read_b128 v[244:247], v177 offset:20480
	ds_read_b128 v[202:205], v177 offset:32768
	ds_read_b128 v[206:209], v162 offset:1024
	s_waitcnt lgkmcnt(0)
	v_mfma_f32_32x32x16_bf16 v[82:97], v[244:247], v[206:209], v[82:97]
	v_mfma_f32_32x32x16_bf16 v[66:81], v[202:205], v[206:209], v[66:81]
	ds_read_b128 v[244:247], v178 offset:20480
	ds_read_b128 v[202:205], v178 offset:32768
	ds_read_b128 v[206:209], v162 offset:2048
	s_waitcnt lgkmcnt(0)
	v_mfma_f32_32x32x16_bf16 v[82:97], v[244:247], v[206:209], v[82:97]
	v_mfma_f32_32x32x16_bf16 v[66:81], v[202:205], v[206:209], v[66:81]
	ds_read_b128 v[244:247], v179 offset:20480
	ds_read_b128 v[202:205], v179 offset:32768
	ds_read_b128 v[206:209], v162 offset:3072
	s_waitcnt lgkmcnt(0)
	v_mfma_f32_32x32x16_bf16 v[82:97], v[244:247], v[206:209], v[82:97]
	v_mfma_f32_32x32x16_bf16 v[66:81], v[202:205], v[206:209], v[66:81]
	ds_read_b128 v[244:247], v180 offset:20480
	ds_read_b128 v[202:205], v180 offset:32768
	ds_read_b128 v[206:209], v162 offset:4096
	s_waitcnt lgkmcnt(0)
	v_mfma_f32_32x32x16_bf16 v[82:97], v[244:247], v[206:209], v[82:97]
	v_mfma_f32_32x32x16_bf16 v[66:81], v[202:205], v[206:209], v[66:81]
	ds_read_b128 v[244:247], v181 offset:20480
	ds_read_b128 v[202:205], v181 offset:32768
	ds_read_b128 v[206:209], v162 offset:5120
	s_waitcnt lgkmcnt(0)
	v_mfma_f32_32x32x16_bf16 v[82:97], v[244:247], v[206:209], v[82:97]
	v_mfma_f32_32x32x16_bf16 v[66:81], v[202:205], v[206:209], v[66:81]
	ds_read_b128 v[244:247], v182 offset:20480
	ds_read_b128 v[202:205], v182 offset:32768
	ds_read_b128 v[206:209], v162 offset:6144
	s_waitcnt lgkmcnt(0)
	v_mfma_f32_32x32x16_bf16 v[82:97], v[244:247], v[206:209], v[82:97]
	v_mfma_f32_32x32x16_bf16 v[66:81], v[202:205], v[206:209], v[66:81]
	ds_read_b128 v[244:247], v183 offset:20480
	ds_read_b128 v[202:205], v183 offset:32768
	ds_read_b128 v[206:209], v162 offset:7168
	s_waitcnt lgkmcnt(0)
	v_mfma_f32_32x32x16_bf16 v[82:97], v[244:247], v[206:209], v[82:97]
	v_mfma_f32_32x32x16_bf16 v[66:81], v[202:205], v[206:209], v[66:81]
	ds_read_b64_tr_b16 v[200:201], v165 offset:0x0
	ds_read_b64_tr_b16 v[202:203], v165 offset:0x800
	ds_read_b64_tr_b16 v[204:205], v165 offset:0x1000
	ds_read_b64_tr_b16 v[206:207], v165 offset:0x1800
	ds_read_b64_tr_b16 v[208:209], v165 offset:0x2000
	ds_read_b64_tr_b16 v[210:211], v165 offset:0x2800
	ds_read_b64_tr_b16 v[222:223], v165 offset:0x3000
	ds_read_b64_tr_b16 v[224:225], v165 offset:0x3800
	s_waitcnt lgkmcnt(0)
	v_mfma_f32_32x32x16_bf16 v[2:17], v[152:155], v[200:203], v[2:17]
	ds_read_b64_tr_b16 v[200:201], v165 offset:0x200
	ds_read_b64_tr_b16 v[202:203], v165 offset:0xa00
	v_exp_f32_e32 v82, v82
	v_exp_f32_e32 v83, v83
	v_exp_f32_e32 v84, v84
	v_exp_f32_e32 v85, v85
	v_exp_f32_e32 v86, v86
	v_add_f32_e32 v252, v82, v83
	v_mfma_f32_32x32x16_bf16 v[2:17], v[156:159], v[204:207], v[2:17]
	ds_read_b64_tr_b16 v[204:205], v165 offset:0x1200
	ds_read_b64_tr_b16 v[206:207], v165 offset:0x1a00
	v_exp_f32_e32 v87, v87
	v_add_f32_e32 v252, v84, v252
	v_exp_f32_e32 v88, v88
	v_add_f32_e32 v252, v85, v252
	v_cvt_pk_bf16_f32 v134, v82, v83
	v_mfma_f32_32x32x16_bf16 v[2:17], v[228:231], v[208:211], v[2:17]
	ds_read_b64_tr_b16 v[208:209], v165 offset:0x2200
	ds_read_b64_tr_b16 v[210:211], v165 offset:0x2a00
	v_exp_f32_e32 v89, v89
	v_add_f32_e32 v252, v86, v252
	v_exp_f32_e32 v90, v90
	v_add_f32_e32 v252, v87, v252
	v_cvt_pk_bf16_f32 v135, v84, v85
	v_exp_f32_e32 v91, v91
	v_mfma_f32_32x32x16_bf16 v[2:17], v[248:251], v[222:225], v[2:17]
	ds_read_b64_tr_b16 v[222:223], v165 offset:0x3200
	ds_read_b64_tr_b16 v[224:225], v165 offset:0x3a00
	v_add_f32_e32 v252, v88, v252
	v_exp_f32_e32 v92, v92
	v_add_f32_e32 v252, v89, v252
	v_cvt_pk_bf16_f32 v136, v86, v87
	v_exp_f32_e32 v93, v93
	s_waitcnt lgkmcnt(0)
; #define SBAR() __builtin_amdgcn_sched_barrier(0)
; DI void finishSM(f32x16& p0, f32x16& p1, float alpha, float& l_reg, bf16x8& pa0, bf16x8& pa1, bf16x8& pa2, bf16x8& pa3) {
; #pragma unroll
;   for (int r = 0; r < 16; ++r) p1[r] = __builtin_amdgcn_exp2f(p1[r]);
;   float ps = 0;
; #pragma unroll
;   for (int r = 0; r < 16; ++r) ps += p0[r];
; #pragma unroll
;   for (int r = 0; r < 16; ++r) ps += p1[r];
;   { auto rr = __builtin_amdgcn_permlane32_swap(__float_as_uint(ps), __float_as_uint(ps), false, false);
;     ps = __uint_as_float(rr[0]) + __uint_as_float(rr[1]); }
;   l_reg = l_reg * alpha + ps;
;     ...
;   PK4(p0, 0, pa0); PK4(p0, 8, pa1); PK4(p1, 0, pa2); PK4(p1, 8, pa3);
; DI int v_st(int k, int c) { const int kk = (k & ~0xC) | ((k & 4) << 1) | ((k & 8) >> 1); return ((kk >> 3) * 4 + (c >> 5)) * 512 + ((kk & 7) * 32 + (c & 31)) * 2; }
; DI int v_rd_base(int lane) { return ((lane & 3) << 3) | (((lane >> 2) & 3) << 6) | (((lane >> 4) & 1) << 5) | (((lane >> 5) & 1) << 8); }
; template <int OFF> DI s16x4 tr_read(int vb) { s16x4 r; asm volatile("ds_read_b64_tr_b16 %0, %1 offset:%2" : "=&v"(r) : "v"(vb), "i"(OFF) : "memory"); return r; }
; template <int D0> DI void pv_one(f32x16& od, int vb, bf16x8 pa0, bf16x8 pa1, bf16x8 pa2, bf16x8 pa3) {
;   const s16x4 l0 = tr_read<v_rd_off(D0, 0, 0)>(vb), h0 = tr_read<v_rd_off(D0, 0, 1)>(vb), l1 = tr_read<v_rd_off(D0, 1, 0)>(vb), h1 = tr_read<v_rd_off(D0, 1, 1)>(vb);
;   const s16x4 l2 = tr_read<v_rd_off(D0, 2, 0)>(vb), h2 = tr_read<v_rd_off(D0, 2, 1)>(vb), l3 = tr_read<v_rd_off(D0, 3, 0)>(vb), h3 = tr_read<v_rd_off(D0, 3, 1)>(vb);
;   asm volatile("s_waitcnt lgkmcnt(0)" ::: "memory"); SBAR();
;     ...
;   od = __builtin_amdgcn_mfma_f32_32x32x16_bf16(pa0, PK(l0, h0), od, 0, 0, 0);
;   od = __builtin_amdgcn_mfma_f32_32x32x16_bf16(pa1, PK(l1, h1), od, 0, 0, 0);
;   od = __builtin_amdgcn_mfma_f32_32x32x16_bf16(pa2, PK(l2, h2), od, 0, 0, 0);
;   od = __builtin_amdgcn_mfma_f32_32x32x16_bf16(pa3, PK(l3, h3), od, 0, 0, 0);
;     ...
; }
; DI void pv_d0(f32x16* o, int vb, bf16x8 pa0, bf16x8 pa1, bf16x8 pa2, bf16x8 pa3) {
;   pv_one<0>(o[0], vb, pa0, pa1, pa2, pa3); pv_one<1>(o[1], vb, pa0, pa1, pa2, pa3); pv_one<2>(o[2], vb, pa0, pa1, pa2, pa3); pv_one<3>(o[3], vb, pa0, pa1, pa2, pa3);
; }
	v_mfma_f32_32x32x16_bf16 v[50:65], v[152:155], v[200:203], v[50:65]
	ds_read_b64_tr_b16 v[200:201], v165 offset:0x400
	ds_read_b64_tr_b16 v[202:203], v165 offset:0xc00
	v_add_f32_e32 v252, v90, v252
	v_exp_f32_e32 v94, v94
	v_add_f32_e32 v252, v91, v252
	v_cvt_pk_bf16_f32 v137, v88, v89
	v_exp_f32_e32 v95, v95
	v_add_f32_e32 v252, v92, v252
	v_mfma_f32_32x32x16_bf16 v[50:65], v[156:159], v[204:207], v[50:65]
	ds_read_b64_tr_b16 v[204:205], v165 offset:0x1400
	ds_read_b64_tr_b16 v[206:207], v165 offset:0x1c00
	v_exp_f32_e32 v96, v96
	v_add_f32_e32 v252, v93, v252
	v_cvt_pk_bf16_f32 v138, v90, v91
	v_exp_f32_e32 v97, v97
	v_add_f32_e32 v252, v94, v252
	v_mfma_f32_32x32x16_bf16 v[50:65], v[228:231], v[208:211], v[50:65]
	ds_read_b64_tr_b16 v[208:209], v165 offset:0x2400
	ds_read_b64_tr_b16 v[210:211], v165 offset:0x2c00
	v_exp_f32_e32 v66, v66
	v_add_f32_e32 v252, v95, v252
	v_cvt_pk_bf16_f32 v139, v92, v93
	v_permlane32_swap_b32_e32 v134, v136
	v_exp_f32_e32 v67, v67
	v_add_f32_e32 v252, v96, v252
	v_mfma_f32_32x32x16_bf16 v[50:65], v[248:251], v[222:225], v[50:65]
	ds_read_b64_tr_b16 v[222:223], v165 offset:0x3400
	ds_read_b64_tr_b16 v[224:225], v165 offset:0x3c00
	v_permlane32_swap_b32_e32 v135, v137
	v_exp_f32_e32 v68, v68
	v_add_f32_e32 v252, v97, v252
	v_cvt_pk_bf16_f32 v140, v94, v95
	v_exp_f32_e32 v69, v69
	s_waitcnt lgkmcnt(0)
	v_mfma_f32_32x32x16_bf16 v[34:49], v[152:155], v[200:203], v[34:49]
	ds_read_b64_tr_b16 v[200:201], v165 offset:0x600
	ds_read_b64_tr_b16 v[202:203], v165 offset:0xe00
	v_add_f32_e32 v252, v66, v252
	v_exp_f32_e32 v70, v70
	v_add_f32_e32 v252, v67, v252
	v_cvt_pk_bf16_f32 v141, v96, v97
	v_exp_f32_e32 v71, v71
	v_add_f32_e32 v252, v68, v252
	v_mfma_f32_32x32x16_bf16 v[34:49], v[156:159], v[204:207], v[34:49]
	ds_read_b64_tr_b16 v[204:205], v165 offset:0x1600
	ds_read_b64_tr_b16 v[206:207], v165 offset:0x1e00
	v_exp_f32_e32 v72, v72
	v_add_f32_e32 v252, v69, v252
	v_cvt_pk_bf16_f32 v214, v66, v67
	v_exp_f32_e32 v73, v73
	v_add_f32_e32 v252, v70, v252
	v_exp_f32_e32 v74, v74
	v_mfma_f32_32x32x16_bf16 v[34:49], v[228:231], v[208:211], v[34:49]
	ds_read_b64_tr_b16 v[208:209], v165 offset:0x2600
	ds_read_b64_tr_b16 v[210:211], v165 offset:0x2e00
	v_add_f32_e32 v252, v71, v252
	v_cvt_pk_bf16_f32 v215, v68, v69
	v_permlane32_swap_b32_e32 v138, v140
	v_exp_f32_e32 v75, v75
	v_add_f32_e32 v252, v72, v252
	v_mfma_f32_32x32x16_bf16 v[34:49], v[248:251], v[222:225], v[34:49]
	ds_read_b64_tr_b16 v[222:223], v165 offset:0x3600
	ds_read_b64_tr_b16 v[224:225], v165 offset:0x3e00
	v_permlane32_swap_b32_e32 v139, v141
	v_exp_f32_e32 v76, v76
	v_add_f32_e32 v252, v73, v252
	v_cvt_pk_bf16_f32 v216, v70, v71
	v_exp_f32_e32 v77, v77
	v_add_f32_e32 v252, v74, v252
	s_waitcnt lgkmcnt(0)
	v_mfma_f32_32x32x16_bf16 v[18:33], v[152:155], v[200:203], v[18:33]
	v_exp_f32_e32 v78, v78
	v_add_f32_e32 v252, v75, v252
	v_cvt_pk_bf16_f32 v217, v72, v73
	v_exp_f32_e32 v79, v79
	v_add_f32_e32 v252, v76, v252
	v_mfma_f32_32x32x16_bf16 v[18:33], v[156:159], v[204:207], v[18:33]
	v_exp_f32_e32 v80, v80
	v_add_f32_e32 v252, v77, v252
	v_cvt_pk_bf16_f32 v218, v74, v75
	v_exp_f32_e32 v81, v81
	v_add_f32_e32 v252, v78, v252
	v_add_f32_e32 v252, v79, v252
	v_mfma_f32_32x32x16_bf16 v[18:33], v[228:231], v[208:211], v[18:33]
	v_cvt_pk_bf16_f32 v219, v76, v77
	v_permlane32_swap_b32_e32 v214, v216
	v_add_f32_e32 v252, v80, v252
	v_permlane32_swap_b32_e32 v215, v217
	v_add_f32_e32 v252, v81, v252
	v_mfma_f32_32x32x16_bf16 v[18:33], v[248:251], v[222:225], v[18:33]
	v_cvt_pk_bf16_f32 v220, v78, v79
	v_cvt_pk_bf16_f32 v221, v80, v81
	v_cmp_nge_f32_e32 vcc, 0x453a4f54, v252
	v_add_f32_e32 v166, v227, v252
	v_permlane32_swap_b32_e32 v218, v220
	v_permlane32_swap_b32_e32 v219, v221
	s_barrier
	s_waitcnt vmcnt(0)
	ds_write_b128 v167, v[114:117] offset:16384
	ds_write_b128 v168, v[118:121] offset:16384
	ds_write_b128 v169, v[122:125] offset:57344
	ds_write_b128 v170, v[126:129] offset:57344
	ds_write_b128 v171, v[130:133] offset:57344
	s_nop 1
	v_mov_b32_e32 v130, 1.0
	s_cbranch_vccz .LBB0_756
	ds_read_b128 v[66:69], v172 offset:20480
	ds_read_b128 v[70:73], v172 offset:32768
	ds_read_b128 v[244:247], v173 offset:20480
	ds_read_b128 v[202:205], v173 offset:32768
	s_waitcnt lgkmcnt(3)
	v_mfma_f32_32x32x16_bf16 v[82:97], v[66:69], v[110:113], 0
	s_waitcnt lgkmcnt(2)
	v_mfma_f32_32x32x16_bf16 v[66:81], v[70:73], v[110:113], 0
	s_waitcnt lgkmcnt(1)
	v_mfma_f32_32x32x16_bf16 v[82:97], v[244:247], v[106:109], v[82:97]
	s_waitcnt lgkmcnt(0)
	v_mfma_f32_32x32x16_bf16 v[66:81], v[202:205], v[106:109], v[66:81]
	ds_read_b128 v[244:247], v174 offset:20480
	ds_read_b128 v[202:205], v174 offset:32768
	s_waitcnt lgkmcnt(1)
	v_mfma_f32_32x32x16_bf16 v[82:97], v[244:247], v[102:105], v[82:97]
	s_waitcnt lgkmcnt(0)
	v_mfma_f32_32x32x16_bf16 v[66:81], v[202:205], v[102:105], v[66:81]
	ds_read_b128 v[244:247], v175 offset:20480
	ds_read_b128 v[202:205], v175 offset:32768
	s_waitcnt lgkmcnt(1)
	v_mfma_f32_32x32x16_bf16 v[82:97], v[244:247], v[98:101], v[82:97]
	s_waitcnt lgkmcnt(0)
	v_mfma_f32_32x32x16_bf16 v[66:81], v[202:205], v[98:101], v[66:81]
	ds_read_b128 v[244:247], v176 offset:20480
	ds_read_b128 v[202:205], v176 offset:32768
	ds_read_b128 v[206:209], v162
	s_waitcnt lgkmcnt(0)
	v_mfma_f32_32x32x16_bf16 v[82:97], v[244:247], v[206:209], v[82:97]
	v_mfma_f32_32x32x16_bf16 v[66:81], v[202:205], v[206:209], v[66:81]
	ds_read_b128 v[244:247], v177 offset:20480
	ds_read_b128 v[202:205], v177 offset:32768
	ds_read_b128 v[206:209], v162 offset:1024
	s_waitcnt lgkmcnt(0)
; DI void partialSM(f32x16& p0, f32x16& p1, float& m_reg, float& mn, float& alpha, const float SCALE) {
;   const float C = SCALE * 1.4426950408889634f;
;   float pmax = p0[0];
; #pragma unroll
;   for (int r = 1; r < 16; ++r) pmax = fmaxf(pmax, p0[r]);
; #pragma unroll
;   for (int r = 0; r < 16; ++r) pmax = fmaxf(pmax, p1[r]);
;   { auto rr = __builtin_amdgcn_permlane32_swap(__float_as_uint(pmax), __float_as_uint(pmax), false, false);
;     pmax = fmaxf(__uint_as_float(rr[0]), __uint_as_float(rr[1])); }
;   if (__builtin_expect(__all(pmax - m_reg <= THR / SCALE), 1)) { mn = m_reg; alpha = 1.f; }
;   else { mn = fmaxf(m_reg, pmax); alpha = __builtin_amdgcn_exp2f((m_reg - mn) * C); m_reg = mn; }
;   const float mnC = -mn * C;
; #pragma unroll
;   for (int r = 0; r < 16; ++r) p0[r] = fmaf(p0[r], C, mnC);
; #pragma unroll
;   for (int r = 0; r < 16; ++r) p1[r] = fmaf(p1[r], C, mnC);
; #pragma unroll
;   for (int r = 0; r < 16; ++r) p0[r] = __builtin_amdgcn_exp2f(p0[r]);
; }
; DI void finishSM(f32x16& p0, f32x16& p1, float alpha, float& l_reg, bf16x8& pa0, bf16x8& pa1, bf16x8& pa2, bf16x8& pa3) {
; #pragma unroll
;   for (int r = 0; r < 16; ++r) p1[r] = __builtin_amdgcn_exp2f(p1[r]);
;   float ps = 0;
; #pragma unroll
;   for (int r = 0; r < 16; ++r) ps += p0[r];
; #pragma unroll
;   for (int r = 0; r < 16; ++r) ps += p1[r];
;   { auto rr = __builtin_amdgcn_permlane32_swap(__float_as_uint(ps), __float_as_uint(ps), false, false);
;     ps = __uint_as_float(rr[0]) + __uint_as_float(rr[1]); }
;   l_reg = l_reg * alpha + ps;
;     ...
;   PK4(p0, 0, pa0); PK4(p0, 8, pa1); PK4(p1, 0, pa2); PK4(p1, 8, pa3);
	v_mfma_f32_32x32x16_bf16 v[82:97], v[244:247], v[206:209], v[82:97]
	v_mfma_f32_32x32x16_bf16 v[66:81], v[202:205], v[206:209], v[66:81]
	ds_read_b128 v[244:247], v178 offset:20480
	ds_read_b128 v[202:205], v178 offset:32768
	ds_read_b128 v[206:209], v162 offset:2048
	s_waitcnt lgkmcnt(0)
	v_mfma_f32_32x32x16_bf16 v[82:97], v[244:247], v[206:209], v[82:97]
	v_mfma_f32_32x32x16_bf16 v[66:81], v[202:205], v[206:209], v[66:81]
	ds_read_b128 v[244:247], v179 offset:20480
	ds_read_b128 v[202:205], v179 offset:32768
	ds_read_b128 v[206:209], v162 offset:3072
	s_waitcnt lgkmcnt(0)
	v_mfma_f32_32x32x16_bf16 v[82:97], v[244:247], v[206:209], v[82:97]
	v_mfma_f32_32x32x16_bf16 v[66:81], v[202:205], v[206:209], v[66:81]
	ds_read_b128 v[244:247], v180 offset:20480
	ds_read_b128 v[202:205], v180 offset:32768
	ds_read_b128 v[206:209], v162 offset:4096
	s_waitcnt lgkmcnt(0)
	v_mfma_f32_32x32x16_bf16 v[82:97], v[244:247], v[206:209], v[82:97]
	v_mfma_f32_32x32x16_bf16 v[66:81], v[202:205], v[206:209], v[66:81]
	ds_read_b128 v[244:247], v181 offset:20480
	ds_read_b128 v[202:205], v181 offset:32768
	ds_read_b128 v[206:209], v162 offset:5120
	s_waitcnt lgkmcnt(0)
	v_mfma_f32_32x32x16_bf16 v[82:97], v[244:247], v[206:209], v[82:97]
	v_mfma_f32_32x32x16_bf16 v[66:81], v[202:205], v[206:209], v[66:81]
	ds_read_b128 v[244:247], v182 offset:20480
	ds_read_b128 v[202:205], v182 offset:32768
	ds_read_b128 v[206:209], v162 offset:6144
	s_waitcnt lgkmcnt(0)
	v_mfma_f32_32x32x16_bf16 v[82:97], v[244:247], v[206:209], v[82:97]
	v_mfma_f32_32x32x16_bf16 v[66:81], v[202:205], v[206:209], v[66:81]
	ds_read_b128 v[244:247], v183 offset:20480
	ds_read_b128 v[202:205], v183 offset:32768
	ds_read_b128 v[206:209], v162 offset:7168
	s_waitcnt lgkmcnt(0)
	v_mfma_f32_32x32x16_bf16 v[82:97], v[244:247], v[206:209], v[82:97]
	v_mfma_f32_32x32x16_bf16 v[66:81], v[202:205], v[206:209], v[66:81]
	s_nop 7
	s_nop 7
	v_max3_f32 v131, v82, v83, v84
	v_max3_f32 v132, v85, v86, v87
	v_max3_f32 v131, v131, v88, v89
	v_max3_f32 v132, v132, v90, v91
	v_max3_f32 v131, v131, v92, v93
	v_max3_f32 v132, v132, v94, v95
	v_max3_f32 v131, v131, v96, v97
	v_max3_f32 v132, v132, v66, v67
	v_max3_f32 v131, v131, v68, v69
	v_max3_f32 v132, v132, v70, v71
	v_max3_f32 v131, v131, v72, v73
	v_max3_f32 v132, v132, v74, v75
	v_max3_f32 v131, v131, v76, v77
	v_max3_f32 v132, v132, v78, v79
	v_max3_f32 v131, v131, v80, v81
	v_max_f32_e32 v131, v131, v132
	v_mov_b32_e32 v132, v131
	s_nop 1
	v_permlane32_swap_b32_e32 v131, v132
	v_max_f32_e32 v131, v131, v132
	v_max_f32_e64 v131, -v226, v131
	v_sub_f32_e64 v132, -v226, v131
	v_exp_f32_e32 v130, v132
	v_mul_f32_e32 v226, 0xbf800000, v131
	v_mov_b32_e32 v184, v226
	v_mov_b32_e32 v185, v226
	v_mov_b32_e32 v186, v226
	v_mov_b32_e32 v187, v226
	v_mov_b32_e32 v188, v226
	v_mov_b32_e32 v189, v226
	v_mov_b32_e32 v190, v226
	v_mov_b32_e32 v191, v226
	v_mov_b32_e32 v192, v226
	v_mov_b32_e32 v193, v226
	v_mov_b32_e32 v194, v226
	v_mov_b32_e32 v195, v226
	v_mov_b32_e32 v196, v226
	v_mov_b32_e32 v197, v226
	v_mov_b32_e32 v198, v226
	v_mov_b32_e32 v199, v226
	v_add_f32_e32 v82, v226, v82
	v_add_f32_e32 v83, v226, v83
	v_add_f32_e32 v84, v226, v84
	v_add_f32_e32 v85, v226, v85
	v_add_f32_e32 v86, v226, v86
	v_add_f32_e32 v87, v226, v87
	v_add_f32_e32 v88, v226, v88
	v_add_f32_e32 v89, v226, v89
	v_add_f32_e32 v90, v226, v90
	v_add_f32_e32 v91, v226, v91
	v_add_f32_e32 v92, v226, v92
	v_add_f32_e32 v93, v226, v93
	v_add_f32_e32 v94, v226, v94
	v_add_f32_e32 v95, v226, v95
	v_add_f32_e32 v96, v226, v96
	v_add_f32_e32 v97, v226, v97
	v_add_f32_e32 v66, v226, v66
	v_add_f32_e32 v67, v226, v67
	v_add_f32_e32 v68, v226, v68
	v_add_f32_e32 v69, v226, v69
	v_add_f32_e32 v70, v226, v70
	v_add_f32_e32 v71, v226, v71
	v_add_f32_e32 v72, v226, v72
	v_add_f32_e32 v73, v226, v73
	v_add_f32_e32 v74, v226, v74
	v_add_f32_e32 v75, v226, v75
	v_add_f32_e32 v76, v226, v76
	v_add_f32_e32 v77, v226, v77
	v_add_f32_e32 v78, v226, v78
	v_add_f32_e32 v79, v226, v79
	v_add_f32_e32 v80, v226, v80
	v_add_f32_e32 v81, v226, v81
	v_exp_f32_e32 v82, v82
	v_exp_f32_e32 v83, v83
	v_exp_f32_e32 v84, v84
	v_exp_f32_e32 v85, v85
	v_exp_f32_e32 v86, v86
	v_exp_f32_e32 v87, v87
	v_exp_f32_e32 v88, v88
	v_exp_f32_e32 v89, v89
	v_exp_f32_e32 v90, v90
	v_exp_f32_e32 v91, v91
	v_exp_f32_e32 v92, v92
	v_exp_f32_e32 v93, v93
	v_exp_f32_e32 v94, v94
	v_exp_f32_e32 v95, v95
	v_exp_f32_e32 v96, v96
	v_exp_f32_e32 v97, v97
	v_exp_f32_e32 v66, v66
	v_exp_f32_e32 v67, v67
	v_exp_f32_e32 v68, v68
	v_exp_f32_e32 v69, v69
	v_exp_f32_e32 v70, v70
	v_exp_f32_e32 v71, v71
	v_exp_f32_e32 v72, v72
	v_exp_f32_e32 v73, v73
	v_exp_f32_e32 v74, v74
	v_exp_f32_e32 v75, v75
	v_exp_f32_e32 v76, v76
	v_exp_f32_e32 v77, v77
	v_exp_f32_e32 v78, v78
	v_exp_f32_e32 v79, v79
	v_exp_f32_e32 v80, v80
	v_exp_f32_e32 v81, v81
	s_nop 0
	v_add_f32_e32 v252, v82, v83
	v_add_f32_e32 v252, v84, v252
	v_add_f32_e32 v252, v85, v252
	v_add_f32_e32 v252, v86, v252
	v_add_f32_e32 v252, v87, v252
	v_add_f32_e32 v252, v88, v252
	v_add_f32_e32 v252, v89, v252
	v_add_f32_e32 v252, v90, v252
	v_add_f32_e32 v252, v91, v252
	v_add_f32_e32 v252, v92, v252
	v_add_f32_e32 v252, v93, v252
	v_add_f32_e32 v252, v94, v252
	v_add_f32_e32 v252, v95, v252
	v_add_f32_e32 v252, v96, v252
	v_add_f32_e32 v252, v97, v252
	v_add_f32_e32 v252, v66, v252
	v_add_f32_e32 v252, v67, v252
	v_add_f32_e32 v252, v68, v252
	v_add_f32_e32 v252, v69, v252
	v_add_f32_e32 v252, v70, v252
	v_add_f32_e32 v252, v71, v252
	v_add_f32_e32 v252, v72, v252
	v_add_f32_e32 v252, v73, v252
	v_add_f32_e32 v252, v74, v252
	v_add_f32_e32 v252, v75, v252
	v_add_f32_e32 v252, v76, v252
	v_add_f32_e32 v252, v77, v252
	v_add_f32_e32 v252, v78, v252
	v_add_f32_e32 v252, v79, v252
	v_add_f32_e32 v252, v80, v252
	v_add_f32_e32 v252, v81, v252
	v_fma_f32 v166, v130, v227, v252
	v_cvt_pk_bf16_f32 v134, v82, v83
	v_cvt_pk_bf16_f32 v135, v84, v85
	v_cvt_pk_bf16_f32 v136, v86, v87
	v_cvt_pk_bf16_f32 v137, v88, v89
	v_cvt_pk_bf16_f32 v138, v90, v91
	v_cvt_pk_bf16_f32 v139, v92, v93
	v_cvt_pk_bf16_f32 v140, v94, v95
	v_cvt_pk_bf16_f32 v141, v96, v97
	v_cvt_pk_bf16_f32 v214, v66, v67
	v_cvt_pk_bf16_f32 v215, v68, v69
	v_cvt_pk_bf16_f32 v216, v70, v71
	v_cvt_pk_bf16_f32 v217, v72, v73
	v_cvt_pk_bf16_f32 v218, v74, v75
	v_cvt_pk_bf16_f32 v219, v76, v77
	v_cvt_pk_bf16_f32 v220, v78, v79
	v_cvt_pk_bf16_f32 v221, v80, v81
	s_nop 1
	v_permlane32_swap_b32_e32 v134, v136
	v_permlane32_swap_b32_e32 v135, v137
	v_permlane32_swap_b32_e32 v138, v140
	v_permlane32_swap_b32_e32 v139, v141
	v_permlane32_swap_b32_e32 v214, v216
	v_permlane32_swap_b32_e32 v215, v217
	v_permlane32_swap_b32_e32 v218, v220
	v_permlane32_swap_b32_e32 v219, v221
	s_and_saveexec_b64 s[10:11], s[0:1]
	ds_write_b32 v164, v130 offset:128
	s_or_b64 exec, exec, s[10:11]
	s_waitcnt lgkmcnt(0)
; #define SBAR() __builtin_amdgcn_sched_barrier(0)
; #define RESC(a) do { if (__any((a) < 1.f)) { if (hi == 0) al_l[r32] = (a); asm volatile("s_waitcnt lgkmcnt(0)" ::: "memory"); \
;     _Pragma("unroll") for (int d = 0; d < 4; ++d) _Pragma("unroll") for (int r = 0; r < 16; ++r) o[d][r] *= al_l[crow(r, hi)]; } } while (0)
; template <int DQK, int SDEPTH, bool OUT_BF16, int QREG = DQK / 16, bool OUT_F16 = false> ...
;     ...
;     RESC(alA); __syncthreads();
;   }
;   SBAR(); QKT(pB0, pB1, K_lds + SHM_K);
;   finishSM(pA0, pA1, alA, l_reg, pa0, pa1, pa2, pa3); SBAR();
;   pv_d0(o, vb0, pa0, pa1, pa2, pa3); partialSM(pB0, pB1, m_reg, mnB, alB, SCALE);
	v_add_u32_e32 v126, v143, v0
	ds_read_b128 v[114:117], v126 offset:224
	ds_read_b128 v[118:121], v126 offset:192
	ds_read_b128 v[122:125], v126 offset:160
	ds_read_b128 v[126:129], v126 offset:128
	s_waitcnt lgkmcnt(3)
	v_pk_mul_f32 v[14:15], v[14:15], v[114:115]
	s_waitcnt lgkmcnt(2)
	v_pk_mul_f32 v[10:11], v[10:11], v[118:119]
	s_waitcnt lgkmcnt(1)
	v_pk_mul_f32 v[6:7], v[6:7], v[122:123]
	v_pk_mul_f32 v[16:17], v[16:17], v[116:117]
	v_pk_mul_f32 v[12:13], v[12:13], v[120:121]
	v_pk_mul_f32 v[8:9], v[8:9], v[124:125]
	s_waitcnt lgkmcnt(0)
	v_pk_mul_f32 v[4:5], v[4:5], v[128:129]
	v_pk_mul_f32 v[2:3], v[2:3], v[126:127]
	v_pk_mul_f32 v[62:63], v[62:63], v[114:115]
	v_pk_mul_f32 v[58:59], v[58:59], v[118:119]
	v_pk_mul_f32 v[54:55], v[54:55], v[122:123]
	v_pk_mul_f32 v[64:65], v[64:65], v[116:117]
	v_pk_mul_f32 v[60:61], v[60:61], v[120:121]
	v_pk_mul_f32 v[56:57], v[56:57], v[124:125]
	v_pk_mul_f32 v[52:53], v[52:53], v[128:129]
	v_pk_mul_f32 v[50:51], v[50:51], v[126:127]
	v_pk_mul_f32 v[46:47], v[46:47], v[114:115]
	v_pk_mul_f32 v[42:43], v[42:43], v[118:119]
	v_pk_mul_f32 v[38:39], v[38:39], v[122:123]
	v_pk_mul_f32 v[48:49], v[48:49], v[116:117]
	v_pk_mul_f32 v[44:45], v[44:45], v[120:121]
	v_pk_mul_f32 v[40:41], v[40:41], v[124:125]
	v_pk_mul_f32 v[36:37], v[36:37], v[128:129]
	v_pk_mul_f32 v[34:35], v[34:35], v[126:127]
	v_pk_mul_f32 v[30:31], v[30:31], v[114:115]
	v_pk_mul_f32 v[26:27], v[26:27], v[118:119]
	v_pk_mul_f32 v[22:23], v[22:23], v[122:123]
	v_pk_mul_f32 v[32:33], v[32:33], v[116:117]
	v_pk_mul_f32 v[28:29], v[28:29], v[120:121]
	v_pk_mul_f32 v[24:25], v[24:25], v[124:125]
	v_pk_mul_f32 v[20:21], v[20:21], v[128:129]
	v_pk_mul_f32 v[18:19], v[18:19], v[126:127]
.LBB0_756:
	v_lshl_add_u64 v[144:145], v[144:145], 0, s[52:53]
	v_lshl_add_u64 v[146:147], v[146:147], 0, s[52:53]
	v_lshl_add_u64 v[148:149], v[148:149], 0, s[52:53]
	v_lshl_add_u64 v[150:151], v[150:151], 0, s[54:55]
	s_add_i32 s41, s41, 2
	s_cmp_ge_u32 s41, s40
	s_waitcnt lgkmcnt(0)
	s_barrier
	s_cbranch_scc1 .Lmla_loop_exit
	s_branch .LBB0_748
.Lmla_loop_exit:
	v_mul_f32_e32 v194, 0xbf800000, v226
	v_mov_b32_e32 v166, v227
	v_mov_b32_e32 v97, v227
	s_nop 1
	v_permlane32_swap_b32_e32 v166, v97
	v_add_f32_e32 v166, v166, v97
	v_add_u32_e32 v172, 0xffffd000, v172
	v_add_u32_e32 v173, 0xffffd000, v173
	v_add_u32_e32 v174, 0xffffd000, v174
	v_add_u32_e32 v175, 0xffffd000, v175
	v_add_u32_e32 v176, 0xffffd000, v176
	v_add_u32_e32 v177, 0xffffd000, v177
	v_add_u32_e32 v178, 0xffffd000, v178
	v_add_u32_e32 v179, 0xffffd000, v179
	v_add_u32_e32 v180, 0xffffd000, v180
	v_add_u32_e32 v181, 0xffffd000, v181
	v_add_u32_e32 v182, 0xffffd000, v182
	v_add_u32_e32 v183, 0xffffd000, v183
	v_add_u32_e32 v196, 0xe000, v172
	v_add_u32_e32 v195, 0xe000, v173
	v_add_u32_e32 v193, 0xe000, v174
	v_add_u32_e32 v192, 0xe000, v175
	v_add_u32_e32 v191, 0xe000, v176
	v_add_u32_e32 v190, 0xe000, v177
	v_add_u32_e32 v189, 0xe000, v178
	v_add_u32_e32 v188, 0xe000, v179
	v_add_u32_e32 v187, 0xe000, v180
	v_add_u32_e32 v186, 0xe000, v181
	v_add_u32_e32 v185, 0xe000, v182
	v_add_u32_e32 v184, 0xe000, v183
.LBB0_758:
	ds_read_b128 v[66:69], v196
	ds_read_b128 v[70:73], v196 offset:12288
	s_waitcnt lgkmcnt(1)
	v_mfma_f32_32x32x16_bf16 v[82:97], v[66:69], v[110:113], 0
	s_waitcnt lgkmcnt(0)
	v_mfma_f32_32x32x16_bf16 v[66:81], v[70:73], v[110:113], 0
	ds_read_b128 v[110:113], v195
	ds_read_b128 v[144:147], v195 offset:12288
	s_waitcnt lgkmcnt(1)
	v_mfma_f32_32x32x16_bf16 v[82:97], v[110:113], v[106:109], v[82:97]
	s_waitcnt lgkmcnt(0)
	v_mfma_f32_32x32x16_bf16 v[66:81], v[144:147], v[106:109], v[66:81]
	ds_read_b128 v[106:109], v193
	ds_read_b128 v[110:113], v193 offset:12288
	s_waitcnt lgkmcnt(1)
	v_mfma_f32_32x32x16_bf16 v[82:97], v[106:109], v[102:105], v[82:97]
	s_waitcnt lgkmcnt(0)
	v_mfma_f32_32x32x16_bf16 v[66:81], v[110:113], v[102:105], v[66:81]
	ds_read_b128 v[102:105], v192
	ds_read_b128 v[106:109], v192 offset:12288
	s_waitcnt lgkmcnt(1)
	v_mfma_f32_32x32x16_bf16 v[82:97], v[102:105], v[98:101], v[82:97]
	s_waitcnt lgkmcnt(0)
	v_mfma_f32_32x32x16_bf16 v[66:81], v[106:109], v[98:101], v[66:81]
	ds_read_b128 v[98:101], v191
	ds_read_b128 v[102:105], v191 offset:12288
	ds_read_b128 v[106:109], v162
	s_waitcnt lgkmcnt(0)
	v_mfma_f32_32x32x16_bf16 v[82:97], v[98:101], v[106:109], v[82:97]
	v_mfma_f32_32x32x16_bf16 v[66:81], v[102:105], v[106:109], v[66:81]
	ds_read_b128 v[98:101], v190
	ds_read_b128 v[102:105], v190 offset:12288
	ds_read_b128 v[106:109], v162 offset:1024
	s_waitcnt lgkmcnt(0)
	v_mfma_f32_32x32x16_bf16 v[82:97], v[98:101], v[106:109], v[82:97]
	v_mfma_f32_32x32x16_bf16 v[66:81], v[102:105], v[106:109], v[66:81]
	ds_read_b128 v[98:101], v189
	ds_read_b128 v[102:105], v189 offset:12288
	ds_read_b128 v[106:109], v162 offset:2048
	s_waitcnt lgkmcnt(0)
	v_mfma_f32_32x32x16_bf16 v[82:97], v[98:101], v[106:109], v[82:97]
	v_mfma_f32_32x32x16_bf16 v[66:81], v[102:105], v[106:109], v[66:81]
	ds_read_b128 v[98:101], v188
	ds_read_b128 v[102:105], v188 offset:12288
	ds_read_b128 v[106:109], v162 offset:3072
	s_waitcnt lgkmcnt(0)
	v_mfma_f32_32x32x16_bf16 v[82:97], v[98:101], v[106:109], v[82:97]
	v_mfma_f32_32x32x16_bf16 v[66:81], v[102:105], v[106:109], v[66:81]
	ds_read_b128 v[98:101], v187
	ds_read_b128 v[102:105], v187 offset:12288
	ds_read_b128 v[106:109], v162 offset:4096
	s_waitcnt lgkmcnt(0)
	v_mfma_f32_32x32x16_bf16 v[82:97], v[98:101], v[106:109], v[82:97]
	v_mfma_f32_32x32x16_bf16 v[66:81], v[102:105], v[106:109], v[66:81]
	ds_read_b128 v[98:101], v186
	ds_read_b128 v[102:105], v186 offset:12288
	ds_read_b128 v[106:109], v162 offset:5120
	s_waitcnt lgkmcnt(0)
; #define SBAR() __builtin_amdgcn_sched_barrier(0)
; #define RESC(a) do { if (__any((a) < 1.f)) { if (hi == 0) al_l[r32] = (a); asm volatile("s_waitcnt lgkmcnt(0)" ::: "memory"); \
;     _Pragma("unroll") for (int d = 0; d < 4; ++d) _Pragma("unroll") for (int r = 0; r < 16; ++r) o[d][r] *= al_l[crow(r, hi)]; } } while (0)
; DI void partialSM(f32x16& p0, f32x16& p1, float& m_reg, float& mn, float& alpha, const float SCALE) {
;   const float C = SCALE * 1.4426950408889634f;
;   float pmax = p0[0];
; #pragma unroll
;   for (int r = 1; r < 16; ++r) pmax = fmaxf(pmax, p0[r]);
; #pragma unroll
;   for (int r = 0; r < 16; ++r) pmax = fmaxf(pmax, p1[r]);
;   { auto rr = __builtin_amdgcn_permlane32_swap(__float_as_uint(pmax), __float_as_uint(pmax), false, false);
;     pmax = fmaxf(__uint_as_float(rr[0]), __uint_as_float(rr[1])); }
;   if (__builtin_expect(__all(pmax - m_reg <= THR / SCALE), 1)) { mn = m_reg; alpha = 1.f; }
;   else { mn = fmaxf(m_reg, pmax); alpha = __builtin_amdgcn_exp2f((m_reg - mn) * C); m_reg = mn; }
; template <int DQK, int SDEPTH, bool OUT_BF16, int QREG = DQK / 16, bool OUT_F16 = false> ...
;     ...
;   SBAR(); QKT(pB0, pB1, K_lds + SHM_K);
;   finishSM(pA0, pA1, alA, l_reg, pa0, pa1, pa2, pa3); SBAR();
;   pv_d0(o, vb0, pa0, pa1, pa2, pa3); partialSM(pB0, pB1, m_reg, mnB, alB, SCALE);
;   __syncthreads(); RESC(alB);
	v_mfma_f32_32x32x16_bf16 v[82:97], v[98:101], v[106:109], v[82:97]
	v_mfma_f32_32x32x16_bf16 v[66:81], v[102:105], v[106:109], v[66:81]
	ds_read_b128 v[98:101], v185
	ds_read_b128 v[102:105], v185 offset:12288
	ds_read_b128 v[106:109], v162 offset:6144
	s_waitcnt lgkmcnt(0)
	v_mfma_f32_32x32x16_bf16 v[82:97], v[98:101], v[106:109], v[82:97]
	v_mfma_f32_32x32x16_bf16 v[66:81], v[102:105], v[106:109], v[66:81]
	ds_read_b128 v[98:101], v184
	ds_read_b128 v[102:105], v184 offset:12288
	ds_read_b128 v[106:109], v162 offset:7168
	s_waitcnt lgkmcnt(0)
	v_mfma_f32_32x32x16_bf16 v[82:97], v[98:101], v[106:109], v[82:97]
	v_mfma_f32_32x32x16_bf16 v[66:81], v[102:105], v[106:109], v[66:81]
	v_mov_b32_e32 v100, v134
	v_mov_b32_e32 v101, v135
	v_mov_b32_e32 v102, v136
	v_mov_b32_e32 v103, v137
	v_mov_b32_e32 v104, v138
	v_mov_b32_e32 v105, v139
	v_mov_b32_e32 v106, v140
	v_mov_b32_e32 v107, v141
	v_mov_b32_e32 v108, v214
	v_mov_b32_e32 v109, v215
	v_mov_b32_e32 v110, v216
	v_mov_b32_e32 v111, v217
	v_mov_b32_e32 v112, v218
	v_mov_b32_e32 v113, v219
	v_mov_b32_e32 v114, v220
	v_mov_b32_e32 v115, v221
	v_mov_b32_e32 v98, v252
	v_mov_b32_e32 v99, v252
	s_nop 1
	v_permlane32_swap_b32_e32 v98, v99
	ds_read_b64_tr_b16 v[116:117], v163 offset:0
	ds_read_b64_tr_b16 v[118:119], v163 offset:0x800
	ds_read_b64_tr_b16 v[120:121], v163 offset:0x1000
	ds_read_b64_tr_b16 v[122:123], v163 offset:0x1800
	ds_read_b64_tr_b16 v[124:125], v163 offset:0x2000
	ds_read_b64_tr_b16 v[126:127], v163 offset:0x2800
	ds_read_b64_tr_b16 v[132:133], v163 offset:0x3000
	ds_read_b64_tr_b16 v[134:135], v163 offset:0x3800
	s_waitcnt lgkmcnt(0)
	s_nop 0
	v_mfma_f32_32x32x16_bf16 v[2:17], v[100:103], v[116:119], v[2:17]
	ds_read_b64_tr_b16 v[116:117], v163 offset:0x200
	ds_read_b64_tr_b16 v[118:119], v163 offset:0xa00
	v_mfma_f32_32x32x16_bf16 v[2:17], v[104:107], v[120:123], v[2:17]
	ds_read_b64_tr_b16 v[120:121], v163 offset:0x1200
	ds_read_b64_tr_b16 v[122:123], v163 offset:0x1a00
	v_mfma_f32_32x32x16_bf16 v[2:17], v[108:111], v[124:127], v[2:17]
	ds_read_b64_tr_b16 v[124:125], v163 offset:0x2200
	ds_read_b64_tr_b16 v[126:127], v163 offset:0x2a00
	v_mfma_f32_32x32x16_bf16 v[2:17], v[112:115], v[132:135], v[2:17]
	ds_read_b64_tr_b16 v[132:133], v163 offset:0x3200
	ds_read_b64_tr_b16 v[134:135], v163 offset:0x3a00
	s_waitcnt lgkmcnt(0)
	v_mfma_f32_32x32x16_bf16 v[50:65], v[100:103], v[116:119], v[50:65]
	ds_read_b64_tr_b16 v[116:117], v163 offset:0x400
	ds_read_b64_tr_b16 v[118:119], v163 offset:0xc00
	v_mfma_f32_32x32x16_bf16 v[50:65], v[104:107], v[120:123], v[50:65]
	ds_read_b64_tr_b16 v[120:121], v163 offset:0x1400
	ds_read_b64_tr_b16 v[122:123], v163 offset:0x1c00
	v_mfma_f32_32x32x16_bf16 v[50:65], v[108:111], v[124:127], v[50:65]
	ds_read_b64_tr_b16 v[124:125], v163 offset:0x2400
	ds_read_b64_tr_b16 v[126:127], v163 offset:0x2c00
	v_mfma_f32_32x32x16_bf16 v[50:65], v[112:115], v[132:135], v[50:65]
	ds_read_b64_tr_b16 v[132:133], v163 offset:0x3400
	ds_read_b64_tr_b16 v[134:135], v163 offset:0x3c00
	s_waitcnt lgkmcnt(0)
	v_mfma_f32_32x32x16_bf16 v[34:49], v[100:103], v[116:119], v[34:49]
	ds_read_b64_tr_b16 v[116:117], v163 offset:0x600
	ds_read_b64_tr_b16 v[118:119], v163 offset:0xe00
	v_mfma_f32_32x32x16_bf16 v[34:49], v[104:107], v[120:123], v[34:49]
	ds_read_b64_tr_b16 v[120:121], v163 offset:0x1600
	ds_read_b64_tr_b16 v[122:123], v163 offset:0x1e00
	v_mfma_f32_32x32x16_bf16 v[34:49], v[108:111], v[124:127], v[34:49]
	ds_read_b64_tr_b16 v[124:125], v163 offset:0x2600
	ds_read_b64_tr_b16 v[126:127], v163 offset:0x2e00
	v_mfma_f32_32x32x16_bf16 v[34:49], v[112:115], v[132:135], v[34:49]
	ds_read_b64_tr_b16 v[132:133], v163 offset:0x3600
	ds_read_b64_tr_b16 v[134:135], v163 offset:0x3e00
	s_waitcnt lgkmcnt(0)
	v_mfma_f32_32x32x16_bf16 v[18:33], v[100:103], v[116:119], v[18:33]
	v_max_f32_e32 v100, v83, v83
	v_max_f32_e32 v101, v82, v82
	v_max_f32_e32 v100, v101, v100
	v_max3_f32 v100, v100, v84, v85
	v_max3_f32 v100, v100, v86, v87
	v_max3_f32 v100, v100, v88, v89
	v_max3_f32 v100, v100, v90, v91
	v_max3_f32 v100, v100, v92, v93
	v_max3_f32 v100, v100, v94, v95
	v_mfma_f32_32x32x16_bf16 v[18:33], v[104:107], v[120:123], v[18:33]
	v_max3_f32 v100, v100, v96, v97
	v_max3_f32 v100, v100, v66, v67
	v_max3_f32 v100, v100, v68, v69
	v_max3_f32 v100, v100, v70, v71
	v_max3_f32 v100, v100, v72, v73
	v_max3_f32 v100, v100, v74, v75
	v_max3_f32 v100, v100, v76, v77
	v_max3_f32 v100, v100, v78, v79
	v_mfma_f32_32x32x16_bf16 v[18:33], v[108:111], v[124:127], v[18:33]
	v_max3_f32 v100, v100, v80, v81
	v_mov_b32_e32 v101, v100
	s_nop 1
	v_permlane32_swap_b32_e32 v100, v101
	v_max_f32_e32 v101, v101, v101
	v_max_f32_e32 v100, v100, v100
	v_max_f32_e32 v100, v100, v101
	v_sub_f32_e32 v101, v100, v194
	v_cmp_ge_f32_e32 vcc, 0x4138aa3b, v101
	v_max_f32_e32 v101, v194, v194
	v_max_f32_e32 v101, v101, v100
	v_mfma_f32_32x32x16_bf16 v[18:33], v[112:115], v[132:135], v[18:33]
	v_sub_f32_e32 v100, v194, v101
	v_mul_f32_e32 v100, 0x3f800000, v100
	v_exp_f32_e32 v100, v100
	s_cmp_eq_u64 vcc, exec
	s_cselect_b64 s[2:3], -1, 0
	v_cndmask_b32_e64 v100, v100, 1.0, s[2:3]
	v_cmp_gt_f32_e32 vcc, 1.0, v100
	s_barrier
	s_cbranch_vccz .LBB0_762
	s_and_saveexec_b64 s[10:11], s[0:1]
	ds_write_b32 v164, v100 offset:128
	s_or_b64 exec, exec, s[10:11]
	s_waitcnt lgkmcnt(0)
	v_add_u32_e32 v114, v143, v0
	ds_read_b128 v[102:105], v114 offset:224
	ds_read_b128 v[106:109], v114 offset:192
	ds_read_b128 v[110:113], v114 offset:160
	ds_read_b128 v[114:117], v114 offset:128
	s_waitcnt lgkmcnt(3)
	v_pk_mul_f32 v[14:15], v[14:15], v[102:103]
	s_waitcnt lgkmcnt(2)
	v_pk_mul_f32 v[10:11], v[10:11], v[106:107]
	s_waitcnt lgkmcnt(1)
	v_pk_mul_f32 v[6:7], v[6:7], v[110:111]
	v_pk_mul_f32 v[16:17], v[16:17], v[104:105]
	v_pk_mul_f32 v[12:13], v[12:13], v[108:109]
	v_pk_mul_f32 v[8:9], v[8:9], v[112:113]
	s_waitcnt lgkmcnt(0)
	v_pk_mul_f32 v[4:5], v[4:5], v[116:117]
	v_pk_mul_f32 v[2:3], v[2:3], v[114:115]
	v_pk_mul_f32 v[62:63], v[62:63], v[102:103]
	v_pk_mul_f32 v[58:59], v[58:59], v[106:107]
	v_pk_mul_f32 v[54:55], v[54:55], v[110:111]
	v_pk_mul_f32 v[64:65], v[64:65], v[104:105]
	v_pk_mul_f32 v[60:61], v[60:61], v[108:109]
	v_pk_mul_f32 v[56:57], v[56:57], v[112:113]
	v_pk_mul_f32 v[52:53], v[52:53], v[116:117]
	v_pk_mul_f32 v[50:51], v[50:51], v[114:115]
	v_pk_mul_f32 v[46:47], v[46:47], v[102:103]
	v_pk_mul_f32 v[42:43], v[42:43], v[106:107]
	v_pk_mul_f32 v[38:39], v[38:39], v[110:111]
	v_pk_mul_f32 v[48:49], v[48:49], v[104:105]
	v_pk_mul_f32 v[44:45], v[44:45], v[108:109]
	v_pk_mul_f32 v[40:41], v[40:41], v[112:113]
	v_pk_mul_f32 v[36:37], v[36:37], v[116:117]
	v_pk_mul_f32 v[34:35], v[34:35], v[114:115]
	v_pk_mul_f32 v[30:31], v[30:31], v[102:103]
	v_pk_mul_f32 v[26:27], v[26:27], v[106:107]
	v_pk_mul_f32 v[22:23], v[22:23], v[110:111]
	v_pk_mul_f32 v[32:33], v[32:33], v[104:105]
	v_pk_mul_f32 v[28:29], v[28:29], v[108:109]
	v_pk_mul_f32 v[24:25], v[24:25], v[112:113]
	v_pk_mul_f32 v[20:21], v[20:21], v[116:117]
	v_pk_mul_f32 v[18:19], v[18:19], v[114:115]
; #define LAS __attribute__((address_space(3)))
; DI void partialSM(f32x16& p0, f32x16& p1, float& m_reg, float& mn, float& alpha, const float SCALE) {
;     ...
;   const float mnC = -mn * C;
; #pragma unroll
;   for (int r = 0; r < 16; ++r) p0[r] = fmaf(p0[r], C, mnC);
; #pragma unroll
;   for (int r = 0; r < 16; ++r) p1[r] = fmaf(p1[r], C, mnC);
; #pragma unroll
;   for (int r = 0; r < 16; ++r) p0[r] = __builtin_amdgcn_exp2f(p0[r]);
; }
; DI void finishSM(f32x16& p0, f32x16& p1, float alpha, float& l_reg, bf16x8& pa0, bf16x8& pa1, bf16x8& pa2, bf16x8& pa3) {
; #pragma unroll
;   for (int r = 0; r < 16; ++r) p1[r] = __builtin_amdgcn_exp2f(p1[r]);
;   float ps = 0;
; #pragma unroll
;   for (int r = 0; r < 16; ++r) ps += p0[r];
; #pragma unroll
;   for (int r = 0; r < 16; ++r) ps += p1[r];
;   { auto rr = __builtin_amdgcn_permlane32_swap(__float_as_uint(ps), __float_as_uint(ps), false, false);
;     ps = __uint_as_float(rr[0]) + __uint_as_float(rr[1]); }
;   l_reg = l_reg * alpha + ps;
;     ...
;   PK4(p0, 0, pa0); PK4(p0, 8, pa1); PK4(p1, 0, pa2); PK4(p1, 8, pa3);
;     ...
; }
; template <int DQK> DI void qkt(f32x16& p0, f32x16& p1, const LAS char* Ks, const bf16x8* qr, int r32, int hi) {
;   p0 = f32x16{}; p1 = f32x16{};
; #pragma unroll
;   for (int d0 = 0; d0 < DQK / 16; ++d0) { const int cb = (d0 * 16 + hi * 8) * 2;
;     const bf16x8 b0 = *(const LAS bf16x8*)(Ks + kswz<DQK>(r32, cb));
;     const bf16x8 b1 = *(const LAS bf16x8*)(Ks + kswz<DQK>(32 + r32, cb));
;     p0 = __builtin_amdgcn_mfma_f32_32x32x16_bf16(b0, qr[d0], p0, 0, 0, 0);
;     p1 = __builtin_amdgcn_mfma_f32_32x32x16_bf16(b1, qr[d0], p1, 0, 0, 0); }
; }
; DI int v_st(int k, int c) { const int kk = (k & ~0xC) | ((k & 4) << 1) | ((k & 8) >> 1); return ((kk >> 3) * 4 + (c >> 5)) * 512 + ((kk & 7) * 32 + (c & 31)) * 2; }
; DI int v_rd_base(int lane) { return ((lane & 3) << 3) | (((lane >> 2) & 3) << 6) | (((lane >> 4) & 1) << 5) | (((lane >> 5) & 1) << 8); }
; template <int OFF> DI s16x4 tr_read(int vb) { s16x4 r; asm volatile("ds_read_b64_tr_b16 %0, %1 offset:%2" : "=&v"(r) : "v"(vb), "i"(OFF) : "memory"); return r; }
; template <int D0> DI void pv_one(f32x16& od, int vb, bf16x8 pa0, bf16x8 pa1, bf16x8 pa2, bf16x8 pa3) {
;   const s16x4 l0 = tr_read<v_rd_off(D0, 0, 0)>(vb), h0 = tr_read<v_rd_off(D0, 0, 1)>(vb), l1 = tr_read<v_rd_off(D0, 1, 0)>(vb), h1 = tr_read<v_rd_off(D0, 1, 1)>(vb);
.LBB0_762:
	v_cndmask_b32_e64 v101, v101, v194, s[2:3]
	v_mul_f32_e32 v101, 0xbf800000, v101
	v_fmamk_f32 v82, v82, 0x3f800000, v101
	v_fmamk_f32 v83, v83, 0x3f800000, v101
	v_fmamk_f32 v110, v95, 0x3f800000, v101
	v_fmamk_f32 v95, v76, 0x3f800000, v101
	v_exp_f32_e32 v76, v82
	v_fmamk_f32 v84, v84, 0x3f800000, v101
	v_fmamk_f32 v111, v96, 0x3f800000, v101
	v_fmamk_f32 v96, v77, 0x3f800000, v101
	v_exp_f32_e32 v77, v83
	v_fmamk_f32 v85, v85, 0x3f800000, v101
	v_fmamk_f32 v112, v97, 0x3f800000, v101
	v_fmamk_f32 v97, v78, 0x3f800000, v101
	v_exp_f32_e32 v78, v84
	v_fmamk_f32 v86, v86, 0x3f800000, v101
	v_fmamk_f32 v66, v66, 0x3f800000, v101
	v_exp_f32_e32 v82, v85
	v_fmamk_f32 v102, v87, 0x3f800000, v101
	v_fmamk_f32 v103, v88, 0x3f800000, v101
	v_fmamk_f32 v104, v89, 0x3f800000, v101
	v_fmamk_f32 v105, v90, 0x3f800000, v101
	v_fmamk_f32 v106, v91, 0x3f800000, v101
	v_fmamk_f32 v107, v92, 0x3f800000, v101
	v_fmamk_f32 v108, v93, 0x3f800000, v101
	v_fmamk_f32 v109, v94, 0x3f800000, v101
	v_fmamk_f32 v67, v67, 0x3f800000, v101
	v_fmamk_f32 v87, v68, 0x3f800000, v101
	v_fmamk_f32 v88, v69, 0x3f800000, v101
	v_fmamk_f32 v89, v70, 0x3f800000, v101
	v_fmamk_f32 v90, v71, 0x3f800000, v101
	v_fmamk_f32 v91, v72, 0x3f800000, v101
	v_fmamk_f32 v92, v73, 0x3f800000, v101
	v_fmamk_f32 v93, v74, 0x3f800000, v101
	v_fmamk_f32 v94, v75, 0x3f800000, v101
	v_exp_f32_e32 v83, v86
	v_fmamk_f32 v79, v79, 0x3f800000, v101
	v_fmamk_f32 v80, v80, 0x3f800000, v101
	v_fmac_f32_e32 v101, 0x3f800000, v81
	v_exp_f32_e32 v81, v66
	v_add_f32_e32 v66, 0, v76
	v_exp_f32_e32 v84, v102
	v_add_f32_e32 v66, v77, v66
	v_exp_f32_e32 v85, v103
	v_add_f32_e32 v66, v78, v66
	v_exp_f32_e32 v86, v104
	v_add_f32_e32 v66, v82, v66
	v_exp_f32_e32 v68, v105
	v_add_f32_e32 v66, v83, v66
	v_exp_f32_e32 v69, v106
	v_add_f32_e32 v66, v84, v66
	v_exp_f32_e32 v70, v107
	v_add_f32_e32 v66, v85, v66
	v_exp_f32_e32 v71, v108
	v_add_f32_e32 v66, v86, v66
	v_exp_f32_e32 v72, v109
	v_add_f32_e32 v66, v68, v66
	v_exp_f32_e32 v73, v110
	v_add_f32_e32 v66, v69, v66
	v_exp_f32_e32 v74, v111
	v_add_f32_e32 v66, v70, v66
	v_exp_f32_e32 v75, v112
	v_add_f32_e32 v66, v71, v66
	v_add_f32_e32 v66, v72, v66
	v_exp_f32_e32 v102, v67
	v_add_f32_e32 v66, v73, v66
	v_exp_f32_e32 v87, v87
	v_add_f32_e32 v66, v74, v66
	v_exp_f32_e32 v88, v88
	v_add_f32_e32 v66, v75, v66
	v_exp_f32_e32 v89, v89
	v_add_f32_e32 v66, v81, v66
	v_exp_f32_e32 v90, v90
	v_add_f32_e32 v66, v102, v66
	v_exp_f32_e32 v91, v91
	v_add_f32_e32 v66, v87, v66
	v_exp_f32_e32 v92, v92
	v_add_f32_e32 v66, v88, v66
	v_exp_f32_e32 v93, v93
	v_add_f32_e32 v66, v89, v66
	v_exp_f32_e32 v94, v94
	v_add_f32_e32 v66, v90, v66
	v_exp_f32_e32 v95, v95
	v_add_f32_e32 v66, v91, v66
	v_exp_f32_e32 v96, v96
	v_add_f32_e32 v66, v92, v66
	v_exp_f32_e32 v97, v97
	v_add_f32_e32 v66, v93, v66
	v_exp_f32_e32 v103, v79
	v_add_f32_e32 v66, v94, v66
	v_exp_f32_e32 v104, v80
	v_add_f32_e32 v66, v95, v66
	v_exp_f32_e32 v101, v101
	v_add_f32_e32 v66, v96, v66
	v_add_f32_e32 v66, v97, v66
	v_add_f32_e32 v66, v103, v66
	v_add_f32_e32 v66, v104, v66
	v_add_f32_e32 v66, v101, v66
	v_mov_b32_e32 v67, v66
	s_nop 1
	v_permlane32_swap_b32_e32 v66, v67
	v_cvt_pk_bf16_f32 v76, v76, v77
	v_cvt_pk_bf16_f32 v77, v78, v82
	v_cvt_pk_bf16_f32 v78, v83, v84
	v_cvt_pk_bf16_f32 v79, v85, v86
	v_cvt_pk_bf16_f32 v68, v68, v69
	v_cvt_pk_bf16_f32 v69, v70, v71
	v_cvt_pk_bf16_f32 v70, v72, v73
	v_cvt_pk_bf16_f32 v71, v74, v75
	v_cvt_pk_bf16_f32 v72, v81, v102
	v_cvt_pk_bf16_f32 v73, v87, v88
	v_cvt_pk_bf16_f32 v74, v89, v90
	v_cvt_pk_bf16_f32 v75, v91, v92
	v_cvt_pk_bf16_f32 v80, v93, v94
	v_cvt_pk_bf16_f32 v81, v95, v96
	v_cvt_pk_bf16_f32 v82, v97, v103
	v_cvt_pk_bf16_f32 v83, v104, v101
	v_permlane32_swap_b32_e32 v76, v78
	v_permlane32_swap_b32_e32 v77, v79
	v_permlane32_swap_b32_e32 v68, v70
	v_permlane32_swap_b32_e32 v69, v71
	v_permlane32_swap_b32_e32 v72, v74
	v_permlane32_swap_b32_e32 v73, v75
	v_permlane32_swap_b32_e32 v80, v82
	v_permlane32_swap_b32_e32 v81, v83
	ds_read_b64_tr_b16 v[84:85], v165 offset:0
	ds_read_b64_tr_b16 v[86:87], v165 offset:0x800
	ds_read_b64_tr_b16 v[88:89], v165 offset:0x1000
	ds_read_b64_tr_b16 v[90:91], v165 offset:0x1800
	ds_read_b64_tr_b16 v[92:93], v165 offset:0x2000
	ds_read_b64_tr_b16 v[94:95], v165 offset:0x2800
	ds_read_b64_tr_b16 v[102:103], v165 offset:0x3000
	ds_read_b64_tr_b16 v[104:105], v165 offset:0x3800
	s_waitcnt lgkmcnt(0)
	s_nop 0
	v_mfma_f32_32x32x16_bf16 v[2:17], v[76:79], v[84:87], v[2:17]
	ds_read_b64_tr_b16 v[84:85], v165 offset:0x200
	ds_read_b64_tr_b16 v[86:87], v165 offset:0xa00
	v_mfma_f32_32x32x16_bf16 v[2:17], v[68:71], v[88:91], v[2:17]
	ds_read_b64_tr_b16 v[88:89], v165 offset:0x1200
	ds_read_b64_tr_b16 v[90:91], v165 offset:0x1a00
	v_mfma_f32_32x32x16_bf16 v[2:17], v[72:75], v[92:95], v[2:17]
	ds_read_b64_tr_b16 v[92:93], v165 offset:0x2200
	ds_read_b64_tr_b16 v[94:95], v165 offset:0x2a00
	v_mfma_f32_32x32x16_bf16 v[2:17], v[80:83], v[102:105], v[2:17]
	ds_read_b64_tr_b16 v[102:103], v165 offset:0x3200
	ds_read_b64_tr_b16 v[104:105], v165 offset:0x3a00
	s_waitcnt lgkmcnt(0)
	v_mfma_f32_32x32x16_bf16 v[50:65], v[76:79], v[84:87], v[50:65]
	ds_read_b64_tr_b16 v[84:85], v165 offset:0x400
	ds_read_b64_tr_b16 v[86:87], v165 offset:0xc00
	v_mfma_f32_32x32x16_bf16 v[50:65], v[68:71], v[88:91], v[50:65]
	ds_read_b64_tr_b16 v[88:89], v165 offset:0x1400
	ds_read_b64_tr_b16 v[90:91], v165 offset:0x1c00
	v_mfma_f32_32x32x16_bf16 v[50:65], v[72:75], v[92:95], v[50:65]
	ds_read_b64_tr_b16 v[92:93], v165 offset:0x2400
	ds_read_b64_tr_b16 v[94:95], v165 offset:0x2c00
	v_mfma_f32_32x32x16_bf16 v[50:65], v[80:83], v[102:105], v[50:65]
	ds_read_b64_tr_b16 v[102:103], v165 offset:0x3400
	ds_read_b64_tr_b16 v[104:105], v165 offset:0x3c00
	s_waitcnt lgkmcnt(0)
	v_mfma_f32_32x32x16_bf16 v[34:49], v[76:79], v[84:87], v[34:49]
	ds_read_b64_tr_b16 v[84:85], v165 offset:0x600
	ds_read_b64_tr_b16 v[86:87], v165 offset:0xe00
	v_mfma_f32_32x32x16_bf16 v[34:49], v[68:71], v[88:91], v[34:49]
	ds_read_b64_tr_b16 v[88:89], v165 offset:0x1600
	ds_read_b64_tr_b16 v[90:91], v165 offset:0x1e00
	v_mfma_f32_32x32x16_bf16 v[34:49], v[72:75], v[92:95], v[34:49]
	ds_read_b64_tr_b16 v[92:93], v165 offset:0x2600
	ds_read_b64_tr_b16 v[94:95], v165 offset:0x2e00
	v_mfma_f32_32x32x16_bf16 v[34:49], v[80:83], v[102:105], v[34:49]
	ds_read_b64_tr_b16 v[102:103], v165 offset:0x3600
	ds_read_b64_tr_b16 v[104:105], v165 offset:0x3e00
	s_waitcnt lgkmcnt(0)
	v_mfma_f32_32x32x16_bf16 v[18:33], v[76:79], v[84:87], v[18:33]
	v_mfma_f32_32x32x16_bf16 v[18:33], v[68:71], v[88:91], v[18:33]
	v_mfma_f32_32x32x16_bf16 v[18:33], v[72:75], v[92:95], v[18:33]
	v_mfma_f32_32x32x16_bf16 v[18:33], v[80:83], v[102:105], v[18:33]
	s_and_saveexec_b64 s[2:3], s[0:1]
	s_cbranch_execz .LBB0_732
	v_add_f32_e32 v68, v98, v99
	v_fmac_f32_e32 v68, v166, v130
	v_add_f32_e32 v66, v66, v67
	v_fmac_f32_e32 v66, v68, v100
	ds_write_b32 v164, v66
	s_branch .LBB0_732
